# GEMM K loops: 8 of 16 LDS-DMA loads per iteration in scalar-base form (2 more VALU address adds removed outright)
# speedup vs baseline: 1.0080x; 1.0080x over previous
.LBB0_118:
	ds_read_b128 v[128:131], v221
	ds_read_b128 v[132:135], v221 offset:1024
	ds_read_b128 v[136:139], v221 offset:2048
	ds_read_b128 v[140:143], v221 offset:3072
	s_add_u32 s8, s6, 0xfff80080
	s_addc_u32 s9, s7, -1
	s_cmp_eq_u32 s53, 28
	s_cselect_b32 s11, s5, s9
	s_cselect_b32 s10, s33, s8
	s_cselect_b32 s9, s43, s52
	s_cselect_b32 s8, s45, s51

	s_add_i32 m0, s58, 0xc000
	ds_read_b128 v[144:147], v222
	ds_read_b128 v[148:151], v222 offset:1024
	ds_read_b128 v[152:155], v222 offset:2048
	ds_read_b128 v[156:159], v222 offset:3072
	ds_read_b128 v[160:163], v222 offset:4096
	ds_read_b128 v[164:167], v222 offset:5120
	ds_read_b128 v[190:193], v222 offset:6144
	ds_read_b128 v[194:197], v222 offset:7168
	global_load_lds_dwordx4 v182, s[6:7]
	s_add_i32 m0, s58, 0xe000
	s_nop 0

	global_load_lds_dwordx4 v184, s[6:7]
	s_waitcnt lgkmcnt(8)
	s_barrier
	s_waitcnt lgkmcnt(0)


	v_mfma_f32_16x16x32_bf16 v[124:127], v[128:131], v[144:147], v[124:127]
	v_mfma_f32_16x16x32_bf16 v[116:119], v[136:139], v[144:147], v[116:119]
	v_mfma_f32_16x16x32_bf16 v[108:111], v[128:131], v[152:155], v[108:111]
	v_mfma_f32_16x16x32_bf16 v[100:103], v[136:139], v[152:155], v[100:103]
	v_mfma_f32_16x16x32_bf16 v[92:95], v[128:131], v[160:163], v[92:95]
	v_mfma_f32_16x16x32_bf16 v[84:87], v[136:139], v[160:163], v[84:87]
	v_mfma_f32_16x16x32_bf16 v[76:79], v[128:131], v[190:193], v[76:79]
	v_mfma_f32_16x16x32_bf16 v[68:71], v[136:139], v[190:193], v[68:71]
	v_mfma_f32_16x16x32_bf16 v[124:127], v[132:135], v[148:151], v[124:127]
	v_mfma_f32_16x16x32_bf16 v[116:119], v[140:143], v[148:151], v[116:119]
	v_mfma_f32_16x16x32_bf16 v[108:111], v[132:135], v[156:159], v[108:111]
	v_mfma_f32_16x16x32_bf16 v[100:103], v[140:143], v[156:159], v[100:103]
	v_mfma_f32_16x16x32_bf16 v[92:95], v[132:135], v[164:167], v[92:95]
	v_mfma_f32_16x16x32_bf16 v[84:87], v[140:143], v[164:167], v[84:87]
	v_mfma_f32_16x16x32_bf16 v[76:79], v[132:135], v[194:197], v[76:79]
	v_mfma_f32_16x16x32_bf16 v[68:71], v[140:143], v[194:197], v[68:71]

	s_barrier
	s_add_i32 s54, s81, s57
	v_lshl_add_u64 v[230:231], s[8:9], 0, v[172:173]
	s_mov_b32 m0, s54
	ds_read_b128 v[198:201], v223
	ds_read_b128 v[202:205], v223 offset:1024
	ds_read_b128 v[206:209], v223 offset:2048
	ds_read_b128 v[226:229], v223 offset:3072
	global_load_lds_dwordx4 v[230:231], off
	s_add_i32 m0, s54, 0x2000
	v_lshl_add_u64 v[232:233], s[8:9], 0, v[174:175]

	global_load_lds_dwordx4 v[232:233], off
	s_barrier
	s_waitcnt lgkmcnt(0)


	v_mfma_f32_16x16x32_bf16 v[120:123], v[198:201], v[144:147], v[120:123]
	v_mfma_f32_16x16x32_bf16 v[112:115], v[206:209], v[144:147], v[112:115]
	v_mfma_f32_16x16x32_bf16 v[104:107], v[198:201], v[152:155], v[104:107]
	v_mfma_f32_16x16x32_bf16 v[96:99], v[206:209], v[152:155], v[96:99]
	v_mfma_f32_16x16x32_bf16 v[88:91], v[198:201], v[160:163], v[88:91]
	v_mfma_f32_16x16x32_bf16 v[80:83], v[206:209], v[160:163], v[80:83]
	v_mfma_f32_16x16x32_bf16 v[72:75], v[198:201], v[190:193], v[72:75]
	v_mfma_f32_16x16x32_bf16 v[64:67], v[206:209], v[190:193], v[64:67]
	v_mfma_f32_16x16x32_bf16 v[120:123], v[202:205], v[148:151], v[120:123]
	v_mfma_f32_16x16x32_bf16 v[112:115], v[226:229], v[148:151], v[112:115]
	v_mfma_f32_16x16x32_bf16 v[104:107], v[202:205], v[156:159], v[104:107]
	v_mfma_f32_16x16x32_bf16 v[96:99], v[226:229], v[156:159], v[96:99]
	v_mfma_f32_16x16x32_bf16 v[88:91], v[202:205], v[164:167], v[88:91]
	v_mfma_f32_16x16x32_bf16 v[80:83], v[226:229], v[164:167], v[80:83]
	v_mfma_f32_16x16x32_bf16 v[72:75], v[202:205], v[194:197], v[72:75]
	v_mfma_f32_16x16x32_bf16 v[64:67], v[226:229], v[194:197], v[64:67]

	s_mov_b32 m0, s58
	v_lshl_add_u64 v[234:235], s[10:11], 0, v[172:173]
	s_barrier
	ds_read_b128 v[144:147], v222 offset:16384
	ds_read_b128 v[148:151], v222 offset:17408
	ds_read_b128 v[152:155], v222 offset:18432
	ds_read_b128 v[156:159], v222 offset:19456
	ds_read_b128 v[160:163], v222 offset:20480
	ds_read_b128 v[164:167], v222 offset:21504
	ds_read_b128 v[190:193], v222 offset:22528
	ds_read_b128 v[194:197], v222 offset:23552
	global_load_lds_dwordx4 v[234:235], off
	s_mov_b32 m0, s59
	v_lshl_add_u64 v[236:237], s[10:11], 0, v[174:175]

	global_load_lds_dwordx4 v[236:237], off
	s_barrier
	s_waitcnt lgkmcnt(0)


	v_mfma_f32_16x16x32_bf16 v[60:63], v[128:131], v[144:147], v[60:63]
	v_mfma_f32_16x16x32_bf16 v[52:55], v[136:139], v[144:147], v[52:55]
	v_mfma_f32_16x16x32_bf16 v[44:47], v[128:131], v[152:155], v[44:47]
	v_mfma_f32_16x16x32_bf16 v[36:39], v[136:139], v[152:155], v[36:39]
	v_mfma_f32_16x16x32_bf16 v[28:31], v[128:131], v[160:163], v[28:31]
	v_mfma_f32_16x16x32_bf16 v[20:23], v[136:139], v[160:163], v[20:23]
	v_mfma_f32_16x16x32_bf16 v[12:15], v[128:131], v[190:193], v[12:15]
	v_mfma_f32_16x16x32_bf16 v[4:7], v[136:139], v[190:193], v[4:7]
	v_mfma_f32_16x16x32_bf16 v[60:63], v[132:135], v[148:151], v[60:63]
	v_mfma_f32_16x16x32_bf16 v[52:55], v[140:143], v[148:151], v[52:55]
	v_mfma_f32_16x16x32_bf16 v[44:47], v[132:135], v[156:159], v[44:47]
	v_mfma_f32_16x16x32_bf16 v[36:39], v[140:143], v[156:159], v[36:39]
	v_mfma_f32_16x16x32_bf16 v[28:31], v[132:135], v[164:167], v[28:31]
	v_mfma_f32_16x16x32_bf16 v[20:23], v[140:143], v[164:167], v[20:23]
	v_mfma_f32_16x16x32_bf16 v[12:15], v[132:135], v[194:197], v[12:15]
	v_mfma_f32_16x16x32_bf16 v[4:7], v[140:143], v[194:197], v[4:7]

	s_barrier
	s_add_u32 s54, s8, 0x80000
	s_addc_u32 s55, s9, 0
	s_add_i32 vcc_lo, s30, s57
	s_mov_b32 m0, vcc_lo
	s_nop 0

	global_load_lds_dwordx4 v172, s[54:55]
	s_add_i32 m0, vcc_lo, 0x2000
	s_nop 0

	global_load_lds_dwordx4 v174, s[54:55]
	s_waitcnt vmcnt(6)
	s_barrier

	v_mfma_f32_16x16x32_bf16 v[56:59], v[198:201], v[144:147], v[56:59]
	v_mfma_f32_16x16x32_bf16 v[48:51], v[206:209], v[144:147], v[48:51]
	v_mfma_f32_16x16x32_bf16 v[40:43], v[198:201], v[152:155], v[40:43]
	v_mfma_f32_16x16x32_bf16 v[32:35], v[206:209], v[152:155], v[32:35]
	v_mfma_f32_16x16x32_bf16 v[24:27], v[198:201], v[160:163], v[24:27]
	v_mfma_f32_16x16x32_bf16 v[16:19], v[206:209], v[160:163], v[16:19]
	v_mfma_f32_16x16x32_bf16 v[8:11], v[198:201], v[190:193], v[8:11]
	v_mfma_f32_16x16x32_bf16 v[0:3], v[206:209], v[190:193], v[0:3]
	v_mfma_f32_16x16x32_bf16 v[56:59], v[202:205], v[148:151], v[56:59]
	v_mfma_f32_16x16x32_bf16 v[48:51], v[226:229], v[148:151], v[48:51]
	v_mfma_f32_16x16x32_bf16 v[40:43], v[202:205], v[156:159], v[40:43]
	v_mfma_f32_16x16x32_bf16 v[32:35], v[226:229], v[156:159], v[32:35]
	v_mfma_f32_16x16x32_bf16 v[24:27], v[202:205], v[164:167], v[24:27]
	v_mfma_f32_16x16x32_bf16 v[16:19], v[226:229], v[164:167], v[16:19]
	v_mfma_f32_16x16x32_bf16 v[8:11], v[202:205], v[194:197], v[8:11]
	v_mfma_f32_16x16x32_bf16 v[0:3], v[226:229], v[194:197], v[0:3]

	s_add_i32 s54, 0, 0x18000
	v_add_u32_e32 v140, s54, v179
	s_barrier
	ds_read_b128 v[128:131], v140
	ds_read_b128 v[132:135], v140 offset:1024
	ds_read_b128 v[136:139], v140 offset:2048
	ds_read_b128 v[140:143], v140 offset:3072
	s_add_u32 s10, s10, 0x80000
	s_addc_u32 s11, s11, 0
	s_mov_b32 m0, s2

	ds_read_b128 v[144:147], v222 offset:32768
	ds_read_b128 v[148:151], v222 offset:33792
	ds_read_b128 v[152:155], v222 offset:34816
	ds_read_b128 v[156:159], v222 offset:35840
	ds_read_b128 v[160:163], v222 offset:36864
	ds_read_b128 v[164:167], v222 offset:37888
	ds_read_b128 v[190:193], v222 offset:38912
	ds_read_b128 v[194:197], v222 offset:39936
	global_load_lds_dwordx4 v172, s[10:11]
	s_mov_b32 m0, s3
	s_nop 0

	global_load_lds_dwordx4 v174, s[10:11]
	s_waitcnt lgkmcnt(8)
	s_barrier
	s_waitcnt lgkmcnt(0)


	v_mfma_f32_16x16x32_bf16 v[124:127], v[128:131], v[144:147], v[124:127]
	v_mfma_f32_16x16x32_bf16 v[116:119], v[136:139], v[144:147], v[116:119]
	v_mfma_f32_16x16x32_bf16 v[108:111], v[128:131], v[152:155], v[108:111]
	v_mfma_f32_16x16x32_bf16 v[100:103], v[136:139], v[152:155], v[100:103]
	v_mfma_f32_16x16x32_bf16 v[92:95], v[128:131], v[160:163], v[92:95]
	v_mfma_f32_16x16x32_bf16 v[84:87], v[136:139], v[160:163], v[84:87]
	v_mfma_f32_16x16x32_bf16 v[76:79], v[128:131], v[190:193], v[76:79]
	v_mfma_f32_16x16x32_bf16 v[68:71], v[136:139], v[190:193], v[68:71]
	v_mfma_f32_16x16x32_bf16 v[124:127], v[132:135], v[148:151], v[124:127]
	v_mfma_f32_16x16x32_bf16 v[116:119], v[140:143], v[148:151], v[116:119]
	v_mfma_f32_16x16x32_bf16 v[108:111], v[132:135], v[156:159], v[108:111]
	v_mfma_f32_16x16x32_bf16 v[100:103], v[140:143], v[156:159], v[100:103]
	v_mfma_f32_16x16x32_bf16 v[92:95], v[132:135], v[164:167], v[92:95]
	v_mfma_f32_16x16x32_bf16 v[84:87], v[140:143], v[164:167], v[84:87]
	v_mfma_f32_16x16x32_bf16 v[76:79], v[132:135], v[194:197], v[76:79]
	v_mfma_f32_16x16x32_bf16 v[68:71], v[140:143], v[194:197], v[68:71]

	s_barrier
	s_add_i32 s10, 0, 0x1c000
	s_add_i32 s11, s54, s57
	v_add_u32_e32 v180, s10, v179
	v_lshl_add_u64 v[230:231], v[230:231], 0, s[20:21]
	s_mov_b32 m0, s11
	ds_read_b128 v[198:201], v180
	ds_read_b128 v[202:205], v180 offset:1024
	ds_read_b128 v[206:209], v180 offset:2048
	ds_read_b128 v[226:229], v180 offset:3072
	global_load_lds_dwordx4 v[230:231], off
	s_add_i32 m0, s11, 0x2000
	v_lshl_add_u64 v[230:231], v[232:233], 0, s[20:21]

	global_load_lds_dwordx4 v[230:231], off
	s_barrier
	s_waitcnt lgkmcnt(0)


	v_mfma_f32_16x16x32_bf16 v[120:123], v[198:201], v[144:147], v[120:123]
	v_mfma_f32_16x16x32_bf16 v[112:115], v[206:209], v[144:147], v[112:115]
	v_mfma_f32_16x16x32_bf16 v[104:107], v[198:201], v[152:155], v[104:107]
	v_mfma_f32_16x16x32_bf16 v[96:99], v[206:209], v[152:155], v[96:99]
	v_mfma_f32_16x16x32_bf16 v[88:91], v[198:201], v[160:163], v[88:91]
	v_mfma_f32_16x16x32_bf16 v[80:83], v[206:209], v[160:163], v[80:83]
	v_mfma_f32_16x16x32_bf16 v[72:75], v[198:201], v[190:193], v[72:75]
	v_mfma_f32_16x16x32_bf16 v[64:67], v[206:209], v[190:193], v[64:67]
	v_mfma_f32_16x16x32_bf16 v[120:123], v[202:205], v[148:151], v[120:123]
	v_mfma_f32_16x16x32_bf16 v[112:115], v[226:229], v[148:151], v[112:115]
	v_mfma_f32_16x16x32_bf16 v[104:107], v[202:205], v[156:159], v[104:107]
	v_mfma_f32_16x16x32_bf16 v[96:99], v[226:229], v[156:159], v[96:99]
	v_mfma_f32_16x16x32_bf16 v[88:91], v[202:205], v[164:167], v[88:91]
	v_mfma_f32_16x16x32_bf16 v[80:83], v[226:229], v[164:167], v[80:83]
	v_mfma_f32_16x16x32_bf16 v[72:75], v[202:205], v[194:197], v[72:75]
	v_mfma_f32_16x16x32_bf16 v[64:67], v[226:229], v[194:197], v[64:67]

	s_mov_b32 m0, s96
	v_lshl_add_u64 v[230:231], v[234:235], 0, s[20:21]
	s_barrier
	ds_read_b128 v[144:147], v222 offset:49152
	ds_read_b128 v[148:151], v222 offset:50176
	ds_read_b128 v[152:155], v222 offset:51200
	ds_read_b128 v[156:159], v222 offset:52224
	ds_read_b128 v[160:163], v222 offset:53248
	ds_read_b128 v[164:167], v222 offset:54272
	ds_read_b128 v[190:193], v222 offset:55296
	ds_read_b128 v[194:197], v222 offset:56320
	global_load_lds_dwordx4 v[230:231], off
	s_mov_b32 m0, s97
	v_lshl_add_u64 v[230:231], v[236:237], 0, s[20:21]

	global_load_lds_dwordx4 v[230:231], off
	s_barrier
	s_waitcnt lgkmcnt(0)


	v_mfma_f32_16x16x32_bf16 v[60:63], v[128:131], v[144:147], v[60:63]
	v_mfma_f32_16x16x32_bf16 v[52:55], v[136:139], v[144:147], v[52:55]
	v_mfma_f32_16x16x32_bf16 v[44:47], v[128:131], v[152:155], v[44:47]
	v_mfma_f32_16x16x32_bf16 v[36:39], v[136:139], v[152:155], v[36:39]
	v_mfma_f32_16x16x32_bf16 v[28:31], v[128:131], v[160:163], v[28:31]
	v_mfma_f32_16x16x32_bf16 v[20:23], v[136:139], v[160:163], v[20:23]
	v_mfma_f32_16x16x32_bf16 v[12:15], v[128:131], v[190:193], v[12:15]
	v_mfma_f32_16x16x32_bf16 v[4:7], v[136:139], v[190:193], v[4:7]
	v_mfma_f32_16x16x32_bf16 v[60:63], v[132:135], v[148:151], v[60:63]
	v_mfma_f32_16x16x32_bf16 v[52:55], v[140:143], v[148:151], v[52:55]
	v_mfma_f32_16x16x32_bf16 v[44:47], v[132:135], v[156:159], v[44:47]
	v_mfma_f32_16x16x32_bf16 v[36:39], v[140:143], v[156:159], v[36:39]
	v_mfma_f32_16x16x32_bf16 v[28:31], v[132:135], v[164:167], v[28:31]
	v_mfma_f32_16x16x32_bf16 v[20:23], v[140:143], v[164:167], v[20:23]
	v_mfma_f32_16x16x32_bf16 v[12:15], v[132:135], v[194:197], v[12:15]
	v_mfma_f32_16x16x32_bf16 v[4:7], v[140:143], v[194:197], v[4:7]

	s_barrier
	s_add_u32 s8, s8, 0x80080
	s_addc_u32 s9, s9, 0
	s_add_i32 s10, s10, s57
	s_mov_b32 m0, s10
	s_nop 0

	global_load_lds_dwordx4 v172, s[8:9]
	s_add_i32 m0, s10, 0x2000
	s_nop 0

	global_load_lds_dwordx4 v174, s[8:9]
	s_waitcnt vmcnt(6)
	s_barrier

	v_mfma_f32_16x16x32_bf16 v[56:59], v[198:201], v[144:147], v[56:59]
	v_mfma_f32_16x16x32_bf16 v[48:51], v[206:209], v[144:147], v[48:51]
	v_mfma_f32_16x16x32_bf16 v[40:43], v[198:201], v[152:155], v[40:43]
	v_mfma_f32_16x16x32_bf16 v[32:35], v[206:209], v[152:155], v[32:35]
	v_mfma_f32_16x16x32_bf16 v[24:27], v[198:201], v[160:163], v[24:27]
	v_mfma_f32_16x16x32_bf16 v[16:19], v[206:209], v[160:163], v[16:19]
	v_mfma_f32_16x16x32_bf16 v[8:11], v[198:201], v[190:193], v[8:11]
	v_mfma_f32_16x16x32_bf16 v[0:3], v[206:209], v[190:193], v[0:3]
	v_mfma_f32_16x16x32_bf16 v[56:59], v[202:205], v[148:151], v[56:59]
	v_mfma_f32_16x16x32_bf16 v[48:51], v[226:229], v[148:151], v[48:51]
	v_mfma_f32_16x16x32_bf16 v[40:43], v[202:205], v[156:159], v[40:43]
	v_mfma_f32_16x16x32_bf16 v[32:35], v[226:229], v[156:159], v[32:35]
	v_mfma_f32_16x16x32_bf16 v[24:27], v[202:205], v[164:167], v[24:27]
	v_mfma_f32_16x16x32_bf16 v[16:19], v[226:229], v[164:167], v[16:19]
	v_mfma_f32_16x16x32_bf16 v[8:11], v[202:205], v[194:197], v[8:11]
	v_mfma_f32_16x16x32_bf16 v[0:3], v[226:229], v[194:197], v[0:3]

	s_add_i32 s53, s53, 2
	s_add_u32 s6, s6, 0x100
	s_addc_u32 s7, s7, 0
	s_add_u32 s51, s51, 0x100
	s_addc_u32 s52, s52, 0
	s_cmp_gt_u32 s53, 29
	s_barrier
	s_cbranch_scc0 .LBB0_118
	v_mov_b32_e32 v142, v210
	v_mov_b32_e32 v143, v169
	s_lshl_b32 s33, s4, 8
	s_add_i32 s33, s33, s34
	v_lshl_add_u32 v133, v142, 4, v143
	v_ashrrev_i32_e32 v198, 2, v133
	v_and_b32_e32 v192, 3, v143
	v_and_b32_e32 v128, -4, v133
	s_cmp_gt_i32 s4, 30
	v_lshl_add_u32 v226, v192, 6, v128
	v_add_u32_e32 v190, s33, v198
	s_cselect_b64 s[52:53], -1, 0
	s_cmp_gt_i32 s50, 8
	s_mov_b64 s[4:5], -1
	s_cbranch_scc0 .LBB0_419
	s_cmp_lg_u32 s50, 9
	s_cbranch_scc0 .LBB0_225
	s_cmp_gt_u32 s50, 25
	s_cbranch_scc0 .LBB0_127
	v_mul_f32_e32 v130, 0xbfb8aa3b, v120
	v_mul_f32_e32 v131, 0xbfb8aa3b, v121
	v_mul_f32_e32 v132, 0xbfb8aa3b, v122
	v_mul_f32_e32 v134, 0xbfb8aa3b, v123
	v_mul_f32_e32 v135, 0xbfb8aa3b, v112
	v_mul_f32_e32 v136, 0xbfb8aa3b, v113
	v_mul_f32_e32 v137, 0xbfb8aa3b, v114
	v_mul_f32_e32 v138, 0xbfb8aa3b, v115
	v_mul_f32_e32 v139, 0xbfb8aa3b, v104
	v_mul_f32_e32 v140, 0xbfb8aa3b, v105
	v_mul_f32_e32 v141, 0xbfb8aa3b, v106
	v_mul_f32_e32 v144, 0xbfb8aa3b, v107
	v_mul_f32_e32 v145, 0xbfb8aa3b, v96
	v_mul_f32_e32 v146, 0xbfb8aa3b, v97
	v_mul_f32_e32 v147, 0xbfb8aa3b, v98
	v_mul_f32_e32 v148, 0xbfb8aa3b, v99
	v_mul_f32_e32 v149, 0xbfb8aa3b, v88
	v_mul_f32_e32 v150, 0xbfb8aa3b, v89
	v_mul_f32_e32 v151, 0xbfb8aa3b, v90
	v_mul_f32_e32 v152, 0xbfb8aa3b, v91
	v_mul_f32_e32 v153, 0xbfb8aa3b, v80
	v_mul_f32_e32 v154, 0xbfb8aa3b, v81
	v_mul_f32_e32 v155, 0xbfb8aa3b, v82
	v_mul_f32_e32 v180, 0xbfb8aa3b, v83
	v_mul_f32_e32 v206, 0xbfb8aa3b, v72
	v_mul_f32_e32 v207, 0xbfb8aa3b, v73
	v_mul_f32_e32 v208, 0xbfb8aa3b, v74
	v_mul_f32_e32 v209, 0xbfb8aa3b, v75
	v_mul_f32_e32 v227, 0xbfb8aa3b, v64
	v_mul_f32_e32 v228, 0xbfb8aa3b, v65
	v_mul_f32_e32 v229, 0xbfb8aa3b, v66
	v_mul_f32_e32 v230, 0xbfb8aa3b, v67
	v_exp_f32_e32 v205, v130
	v_exp_f32_e32 v204, v131
	v_exp_f32_e32 v203, v132
	v_exp_f32_e32 v202, v134
	v_exp_f32_e32 v200, v135
	v_exp_f32_e32 v199, v136
	v_exp_f32_e32 v197, v137
	v_exp_f32_e32 v196, v138
	v_exp_f32_e32 v195, v139
	v_exp_f32_e32 v194, v140
	v_exp_f32_e32 v193, v141
	v_exp_f32_e32 v167, v144
	v_exp_f32_e32 v166, v145
	v_exp_f32_e32 v165, v146
	v_exp_f32_e32 v164, v147
	v_exp_f32_e32 v163, v148
	v_exp_f32_e32 v162, v149
	v_exp_f32_e32 v161, v150
	v_exp_f32_e32 v160, v151
	v_exp_f32_e32 v159, v152
	v_exp_f32_e32 v158, v153
	v_exp_f32_e32 v157, v154
	v_exp_f32_e32 v156, v155
	v_exp_f32_e32 v155, v180
	v_exp_f32_e32 v154, v206
	v_exp_f32_e32 v153, v207
	v_exp_f32_e32 v152, v208
	v_exp_f32_e32 v151, v209
	v_exp_f32_e32 v150, v227
	v_exp_f32_e32 v149, v228
	v_exp_f32_e32 v148, v229
	v_exp_f32_e32 v147, v230
	v_ashrrev_i32_e32 v191, 31, v190
	s_cmp_lt_u32 s50, 42
	v_lshlrev_b32_e32 v201, 2, v192
	v_lshlrev_b64 v[128:129], 12, v[190:191]
	v_mul_f32_e32 v146, 0xbfb8aa3b, v56
	v_mul_f32_e32 v145, 0xbfb8aa3b, v57
	v_mul_f32_e32 v144, 0xbfb8aa3b, v58
	v_mul_f32_e32 v141, 0xbfb8aa3b, v59
	v_mul_f32_e32 v140, 0xbfb8aa3b, v48
	v_mul_f32_e32 v139, 0xbfb8aa3b, v49
	v_mul_f32_e32 v138, 0xbfb8aa3b, v50
	v_mul_f32_e32 v137, 0xbfb8aa3b, v51
	v_mul_f32_e32 v136, 0xbfb8aa3b, v40
	v_mul_f32_e32 v135, 0xbfb8aa3b, v41
	v_mul_f32_e32 v134, 0xbfb8aa3b, v42
	v_mul_f32_e32 v132, 0xbfb8aa3b, v43
	s_cbranch_scc1 .LBB0_124
	v_mul_f32_e32 v130, 0xbfb8aa3b, v124
	v_mul_f32_e32 v131, 0xbfb8aa3b, v125
	v_mul_f32_e32 v206, 0xbfb8aa3b, v126
	v_mul_f32_e32 v207, 0xbfb8aa3b, v127
	v_exp_f32_e32 v130, v130
	v_exp_f32_e32 v131, v131
	v_exp_f32_e32 v206, v206
	v_exp_f32_e32 v207, v207
	v_add_f32_e32 v130, 1.0, v130
	v_add_f32_e32 v131, 1.0, v131
	v_add_f32_e32 v206, 1.0, v206
	v_add_f32_e32 v207, 1.0, v207
	v_rcp_f32_e32 v130, v130
	v_rcp_f32_e32 v131, v131
	v_rcp_f32_e32 v206, v206
	v_rcp_f32_e32 v207, v207
	s_lshl_b32 s4, s50, 8
	v_cvt_pk_bf16_f32 v130, v130, v131
	s_add_i32 s4, s28, s4
	v_cvt_pk_bf16_f32 v131, v206, v207
	ds_bpermute_b32 v206, v226, v130
	ds_bpermute_b32 v207, v226, v131
	v_or_b32_e32 v180, s4, v201
	v_lshl_add_u64 v[130:131], s[40:41], 0, v[128:129]
	v_lshlrev_b64 v[208:209], 1, v[180:181]
	v_lshl_add_u64 v[130:131], v[130:131], 0, v[208:209]
	s_waitcnt lgkmcnt(0)
	global_store_dwordx2 v[130:131], v[206:207], off
	v_mul_f32_e32 v180, 0xbfb8aa3b, v116
	v_mul_f32_e32 v206, 0xbfb8aa3b, v117
	v_mul_f32_e32 v207, 0xbfb8aa3b, v118
	v_mul_f32_e32 v208, 0xbfb8aa3b, v119
	v_exp_f32_e32 v180, v180
	v_exp_f32_e32 v206, v206
	v_exp_f32_e32 v207, v207
	v_exp_f32_e32 v208, v208
	v_add_f32_e32 v180, 1.0, v180
	v_add_f32_e32 v206, 1.0, v206
	v_add_f32_e32 v207, 1.0, v207
	v_add_f32_e32 v208, 1.0, v208
	v_rcp_f32_e32 v180, v180
	v_rcp_f32_e32 v206, v206
	v_rcp_f32_e32 v207, v207
	v_rcp_f32_e32 v208, v208
	s_mov_b64 s[4:5], 0x10000
	v_cvt_pk_bf16_f32 v180, v180, v206
	ds_bpermute_b32 v206, v226, v180
	v_cvt_pk_bf16_f32 v207, v207, v208
	ds_bpermute_b32 v207, v226, v207
	v_add_f32_e32 v180, 1.0, v205
	v_add_f32_e32 v208, 1.0, v202
	v_rcp_f32_e32 v180, v180
	v_rcp_f32_e32 v208, v208
	s_waitcnt lgkmcnt(0)
	global_store_dwordx2 v[130:131], v[206:207], off offset:32
	v_add_f32_e32 v206, 1.0, v204
	v_add_f32_e32 v207, 1.0, v203
	v_rcp_f32_e32 v206, v206
	v_rcp_f32_e32 v207, v207
	v_mul_f32_e32 v227, 0xbfb8aa3b, v103
	v_exp_f32_e32 v227, v227
	v_cvt_pk_bf16_f32 v180, v180, v206
	v_cvt_pk_bf16_f32 v207, v207, v208
	ds_bpermute_b32 v206, v226, v180
	ds_bpermute_b32 v207, v226, v207
	v_add_f32_e32 v180, 1.0, v200
	v_add_f32_e32 v208, 1.0, v196
	v_rcp_f32_e32 v180, v180
	v_rcp_f32_e32 v208, v208
	s_waitcnt lgkmcnt(0)
	global_store_dwordx2 v[130:131], v[206:207], off offset:256
	v_add_f32_e32 v206, 1.0, v199
	v_add_f32_e32 v207, 1.0, v197
	v_rcp_f32_e32 v206, v206
	v_rcp_f32_e32 v207, v207
	v_add_f32_e32 v227, 1.0, v227
	v_rcp_f32_e32 v227, v227
	v_cvt_pk_bf16_f32 v180, v180, v206
	v_cvt_pk_bf16_f32 v207, v207, v208
	ds_bpermute_b32 v206, v226, v180
	ds_bpermute_b32 v207, v226, v207
	v_mul_f32_e32 v180, 0xbfb8aa3b, v108
	v_mul_f32_e32 v208, 0xbfb8aa3b, v111
	v_exp_f32_e32 v180, v180
	v_exp_f32_e32 v208, v208
	s_waitcnt lgkmcnt(0)
	global_store_dwordx2 v[130:131], v[206:207], off offset:288
	v_mul_f32_e32 v206, 0xbfb8aa3b, v109
	v_mul_f32_e32 v207, 0xbfb8aa3b, v110
	v_exp_f32_e32 v206, v206
	v_exp_f32_e32 v207, v207
	v_add_f32_e32 v180, 1.0, v180
	v_add_f32_e32 v208, 1.0, v208
	v_add_f32_e32 v206, 1.0, v206
	v_add_f32_e32 v207, 1.0, v207
	v_rcp_f32_e32 v180, v180
	v_rcp_f32_e32 v206, v206
	v_rcp_f32_e32 v207, v207
	v_rcp_f32_e32 v208, v208
	v_cvt_pk_bf16_f32 v180, v180, v206
	ds_bpermute_b32 v206, v226, v180
	v_cvt_pk_bf16_f32 v207, v207, v208
	ds_bpermute_b32 v207, v226, v207
	v_lshl_add_u64 v[208:209], v[130:131], 0, s[4:5]
	s_mov_b32 s4, 0x10000
	v_add_co_u32_e32 v228, vcc, s4, v130
	v_mul_f32_e32 v180, 0xbfb8aa3b, v100
	s_nop 0
	v_addc_co_u32_e32 v229, vcc, 0, v131, vcc
	s_waitcnt lgkmcnt(0)
	global_store_dwordx2 v[228:229], v[206:207], off
	v_mul_f32_e32 v206, 0xbfb8aa3b, v101
	v_mul_f32_e32 v207, 0xbfb8aa3b, v102
	v_exp_f32_e32 v180, v180
	v_exp_f32_e32 v206, v206
	v_exp_f32_e32 v207, v207
	s_mov_b64 s[4:5], 0x20000
	v_add_f32_e32 v180, 1.0, v180
	v_add_f32_e32 v206, 1.0, v206
	v_add_f32_e32 v207, 1.0, v207
	v_rcp_f32_e32 v180, v180
	v_rcp_f32_e32 v206, v206
	v_rcp_f32_e32 v207, v207
	v_cvt_pk_bf16_f32 v180, v180, v206
	v_cvt_pk_bf16_f32 v207, v207, v227
	ds_bpermute_b32 v206, v226, v180
	ds_bpermute_b32 v207, v226, v207
	v_add_f32_e32 v180, 1.0, v195
	v_add_f32_e32 v227, 1.0, v167
	v_rcp_f32_e32 v180, v180
	v_rcp_f32_e32 v227, v227
	s_waitcnt lgkmcnt(0)
	global_store_dwordx2 v[208:209], v[206:207], off offset:32
	v_add_f32_e32 v206, 1.0, v194
	v_add_f32_e32 v207, 1.0, v193
	v_rcp_f32_e32 v206, v206
	v_rcp_f32_e32 v207, v207
	v_cvt_pk_bf16_f32 v180, v180, v206
	v_cvt_pk_bf16_f32 v207, v207, v227
	ds_bpermute_b32 v206, v226, v180
	ds_bpermute_b32 v207, v226, v207
	v_add_f32_e32 v180, 1.0, v166
	v_add_f32_e32 v227, 1.0, v163
	v_rcp_f32_e32 v180, v180
	v_rcp_f32_e32 v227, v227
	s_waitcnt lgkmcnt(0)
	global_store_dwordx2 v[208:209], v[206:207], off offset:256
	v_add_f32_e32 v206, 1.0, v165
	v_add_f32_e32 v207, 1.0, v164
	v_rcp_f32_e32 v206, v206
	v_rcp_f32_e32 v207, v207
	v_cvt_pk_bf16_f32 v180, v180, v206
	v_cvt_pk_bf16_f32 v207, v207, v227
	ds_bpermute_b32 v206, v226, v180
	ds_bpermute_b32 v207, v226, v207
	v_mul_f32_e32 v180, 0xbfb8aa3b, v92
	v_exp_f32_e32 v180, v180
	v_mul_f32_e32 v227, 0xbfb8aa3b, v87
	v_exp_f32_e32 v227, v227
	s_waitcnt lgkmcnt(0)
	global_store_dwordx2 v[208:209], v[206:207], off offset:288
	v_mul_f32_e32 v206, 0xbfb8aa3b, v93
	v_mul_f32_e32 v207, 0xbfb8aa3b, v94
	v_mul_f32_e32 v208, 0xbfb8aa3b, v95
	v_exp_f32_e32 v206, v206
	v_exp_f32_e32 v207, v207
	v_exp_f32_e32 v208, v208
	v_add_f32_e32 v180, 1.0, v180
	v_add_f32_e32 v206, 1.0, v206
	v_add_f32_e32 v207, 1.0, v207
	v_add_f32_e32 v208, 1.0, v208
	v_rcp_f32_e32 v180, v180
	v_rcp_f32_e32 v206, v206
	v_rcp_f32_e32 v207, v207
	v_rcp_f32_e32 v208, v208
	v_add_f32_e32 v227, 1.0, v227
	v_cvt_pk_bf16_f32 v180, v180, v206
	ds_bpermute_b32 v206, v226, v180
	v_cvt_pk_bf16_f32 v207, v207, v208
	ds_bpermute_b32 v207, v226, v207
	v_lshl_add_u64 v[208:209], v[130:131], 0, s[4:5]
	s_mov_b32 s4, 0x20000
	v_add_co_u32_e32 v228, vcc, s4, v130
	v_mul_f32_e32 v180, 0xbfb8aa3b, v84
	s_nop 0
	v_addc_co_u32_e32 v229, vcc, 0, v131, vcc
	s_waitcnt lgkmcnt(0)
	global_store_dwordx2 v[228:229], v[206:207], off
	v_mul_f32_e32 v206, 0xbfb8aa3b, v85
	v_mul_f32_e32 v207, 0xbfb8aa3b, v86
	v_exp_f32_e32 v180, v180
	v_exp_f32_e32 v206, v206
	v_exp_f32_e32 v207, v207
	v_rcp_f32_e32 v227, v227
	v_add_f32_e32 v180, 1.0, v180
	v_add_f32_e32 v206, 1.0, v206
	v_add_f32_e32 v207, 1.0, v207
	v_rcp_f32_e32 v180, v180
	v_rcp_f32_e32 v206, v206
	v_rcp_f32_e32 v207, v207
	s_mov_b64 s[4:5], 0x30000
	v_cvt_pk_bf16_f32 v180, v180, v206
	v_cvt_pk_bf16_f32 v207, v207, v227
	ds_bpermute_b32 v206, v226, v180
	ds_bpermute_b32 v207, v226, v207
	v_add_f32_e32 v180, 1.0, v162
	v_add_f32_e32 v227, 1.0, v159
	v_rcp_f32_e32 v180, v180
	v_rcp_f32_e32 v227, v227
	s_waitcnt lgkmcnt(0)
	global_store_dwordx2 v[208:209], v[206:207], off offset:32
	v_add_f32_e32 v206, 1.0, v161
	v_add_f32_e32 v207, 1.0, v160
	v_rcp_f32_e32 v206, v206
	v_rcp_f32_e32 v207, v207
	v_cvt_pk_bf16_f32 v180, v180, v206
	v_cvt_pk_bf16_f32 v207, v207, v227
	ds_bpermute_b32 v206, v226, v180
	ds_bpermute_b32 v207, v226, v207
	v_add_f32_e32 v180, 1.0, v158
	v_add_f32_e32 v227, 1.0, v155
	v_rcp_f32_e32 v180, v180
	v_rcp_f32_e32 v227, v227
	s_waitcnt lgkmcnt(0)
	global_store_dwordx2 v[208:209], v[206:207], off offset:256
	v_add_f32_e32 v206, 1.0, v157
	v_add_f32_e32 v207, 1.0, v156
	v_rcp_f32_e32 v206, v206
	v_rcp_f32_e32 v207, v207
	v_cvt_pk_bf16_f32 v180, v180, v206
	v_cvt_pk_bf16_f32 v207, v207, v227
	ds_bpermute_b32 v206, v226, v180
	ds_bpermute_b32 v207, v226, v207
	v_mul_f32_e32 v180, 0xbfb8aa3b, v76
	v_exp_f32_e32 v180, v180
	v_mul_f32_e32 v227, 0xbfb8aa3b, v71
	v_exp_f32_e32 v227, v227
	s_waitcnt lgkmcnt(0)
	global_store_dwordx2 v[208:209], v[206:207], off offset:288
	v_mul_f32_e32 v206, 0xbfb8aa3b, v77
	v_mul_f32_e32 v207, 0xbfb8aa3b, v78
	v_mul_f32_e32 v208, 0xbfb8aa3b, v79
	v_exp_f32_e32 v206, v206
	v_exp_f32_e32 v207, v207
	v_exp_f32_e32 v208, v208
	v_add_f32_e32 v180, 1.0, v180
	v_add_f32_e32 v206, 1.0, v206
	v_add_f32_e32 v207, 1.0, v207
	v_add_f32_e32 v208, 1.0, v208
	v_rcp_f32_e32 v180, v180
	v_rcp_f32_e32 v206, v206
	v_rcp_f32_e32 v207, v207
	v_rcp_f32_e32 v208, v208
	v_add_f32_e32 v227, 1.0, v227
	v_cvt_pk_bf16_f32 v180, v180, v206
	ds_bpermute_b32 v206, v226, v180
	v_cvt_pk_bf16_f32 v207, v207, v208
	ds_bpermute_b32 v207, v226, v207
	v_lshl_add_u64 v[208:209], v[130:131], 0, s[4:5]
	s_mov_b32 s4, 0x30000
	v_add_co_u32_e32 v228, vcc, s4, v130
	v_mul_f32_e32 v180, 0xbfb8aa3b, v68
	s_nop 0
	v_addc_co_u32_e32 v229, vcc, 0, v131, vcc
	s_waitcnt lgkmcnt(0)
	global_store_dwordx2 v[228:229], v[206:207], off
	v_mul_f32_e32 v206, 0xbfb8aa3b, v69
	v_mul_f32_e32 v207, 0xbfb8aa3b, v70
	v_exp_f32_e32 v180, v180
	v_exp_f32_e32 v206, v206
	v_exp_f32_e32 v207, v207
	v_rcp_f32_e32 v227, v227
	v_add_f32_e32 v180, 1.0, v180
	v_add_f32_e32 v206, 1.0, v206
	v_add_f32_e32 v207, 1.0, v207
	v_rcp_f32_e32 v180, v180
	v_rcp_f32_e32 v206, v206
	v_rcp_f32_e32 v207, v207
	s_mov_b64 s[4:5], 0x80000
	v_cvt_pk_bf16_f32 v180, v180, v206
	v_cvt_pk_bf16_f32 v207, v207, v227
	ds_bpermute_b32 v206, v226, v180
	ds_bpermute_b32 v207, v226, v207
	v_add_f32_e32 v180, 1.0, v154
	v_add_f32_e32 v227, 1.0, v151
	v_rcp_f32_e32 v180, v180
	v_rcp_f32_e32 v227, v227
	s_waitcnt lgkmcnt(0)
	global_store_dwordx2 v[208:209], v[206:207], off offset:32
	v_add_f32_e32 v206, 1.0, v153
	v_add_f32_e32 v207, 1.0, v152
	v_rcp_f32_e32 v206, v206
	v_rcp_f32_e32 v207, v207
	v_cvt_pk_bf16_f32 v180, v180, v206
	v_cvt_pk_bf16_f32 v207, v207, v227
	ds_bpermute_b32 v206, v226, v180
	ds_bpermute_b32 v207, v226, v207
	v_add_f32_e32 v180, 1.0, v150
	v_add_f32_e32 v227, 1.0, v147
	v_rcp_f32_e32 v180, v180
	v_rcp_f32_e32 v227, v227
	s_waitcnt lgkmcnt(0)
	global_store_dwordx2 v[208:209], v[206:207], off offset:256
	v_add_f32_e32 v206, 1.0, v149
	v_add_f32_e32 v207, 1.0, v148
	v_rcp_f32_e32 v206, v206
	v_rcp_f32_e32 v207, v207
	v_cvt_pk_bf16_f32 v180, v180, v206
	v_cvt_pk_bf16_f32 v207, v207, v227
	ds_bpermute_b32 v206, v226, v180
	ds_bpermute_b32 v207, v226, v207
	v_mul_f32_e32 v180, 0xbfb8aa3b, v60
	v_exp_f32_e32 v180, v180
	v_mul_f32_e32 v227, 0xbfb8aa3b, v55
	v_exp_f32_e32 v227, v227
	s_waitcnt lgkmcnt(0)
	global_store_dwordx2 v[208:209], v[206:207], off offset:288
	v_mul_f32_e32 v206, 0xbfb8aa3b, v61
	v_mul_f32_e32 v207, 0xbfb8aa3b, v62
	v_mul_f32_e32 v208, 0xbfb8aa3b, v63
	v_exp_f32_e32 v206, v206
	v_exp_f32_e32 v207, v207
	v_exp_f32_e32 v208, v208
	v_add_f32_e32 v180, 1.0, v180
	v_add_f32_e32 v206, 1.0, v206
	v_add_f32_e32 v207, 1.0, v207
	v_add_f32_e32 v208, 1.0, v208
	v_rcp_f32_e32 v180, v180
	v_rcp_f32_e32 v206, v206
	v_rcp_f32_e32 v207, v207
	v_rcp_f32_e32 v208, v208
	v_add_f32_e32 v227, 1.0, v227
	v_cvt_pk_bf16_f32 v180, v180, v206
	ds_bpermute_b32 v206, v226, v180
	v_cvt_pk_bf16_f32 v207, v207, v208
	ds_bpermute_b32 v207, v226, v207
	v_lshl_add_u64 v[208:209], v[130:131], 0, s[4:5]
	s_mov_b32 s4, 0x80000
	v_add_co_u32_e32 v228, vcc, s4, v130
	v_mul_f32_e32 v180, 0xbfb8aa3b, v52
	s_nop 0
	v_addc_co_u32_e32 v229, vcc, 0, v131, vcc
	s_waitcnt lgkmcnt(0)
	global_store_dwordx2 v[228:229], v[206:207], off
	v_mul_f32_e32 v206, 0xbfb8aa3b, v53
	v_mul_f32_e32 v207, 0xbfb8aa3b, v54
	v_exp_f32_e32 v180, v180
	v_exp_f32_e32 v206, v206
	v_exp_f32_e32 v207, v207
	v_rcp_f32_e32 v227, v227
	v_add_f32_e32 v180, 1.0, v180
	v_add_f32_e32 v206, 1.0, v206
	v_add_f32_e32 v207, 1.0, v207
	v_rcp_f32_e32 v180, v180
	v_rcp_f32_e32 v206, v206
	v_rcp_f32_e32 v207, v207
	s_mov_b64 s[4:5], 0x90000
	v_cvt_pk_bf16_f32 v180, v180, v206
	v_cvt_pk_bf16_f32 v207, v207, v227
	ds_bpermute_b32 v206, v226, v180
	ds_bpermute_b32 v207, v226, v207
	v_exp_f32_e32 v180, v146
	v_exp_f32_e32 v227, v141
	s_waitcnt lgkmcnt(0)
	global_store_dwordx2 v[208:209], v[206:207], off offset:32
	v_exp_f32_e32 v206, v145
	v_exp_f32_e32 v207, v144
	v_add_f32_e32 v180, 1.0, v180
	v_add_f32_e32 v227, 1.0, v227
	v_add_f32_e32 v206, 1.0, v206
	v_add_f32_e32 v207, 1.0, v207
	v_rcp_f32_e32 v180, v180
	v_rcp_f32_e32 v206, v206
	v_rcp_f32_e32 v207, v207
	v_rcp_f32_e32 v227, v227
	v_cvt_pk_bf16_f32 v180, v180, v206
	ds_bpermute_b32 v206, v226, v180
	v_cvt_pk_bf16_f32 v207, v207, v227
	ds_bpermute_b32 v207, v226, v207
	v_exp_f32_e32 v180, v140
	v_exp_f32_e32 v227, v137
	s_waitcnt lgkmcnt(0)
	global_store_dwordx2 v[208:209], v[206:207], off offset:256
	v_exp_f32_e32 v206, v139
	v_exp_f32_e32 v207, v138
	v_add_f32_e32 v180, 1.0, v180
	v_add_f32_e32 v227, 1.0, v227
	v_add_f32_e32 v206, 1.0, v206
	v_add_f32_e32 v207, 1.0, v207
	v_rcp_f32_e32 v180, v180
	v_rcp_f32_e32 v206, v206
	v_rcp_f32_e32 v207, v207
	v_rcp_f32_e32 v227, v227
	v_cvt_pk_bf16_f32 v180, v180, v206
	ds_bpermute_b32 v206, v226, v180
	v_cvt_pk_bf16_f32 v207, v207, v227
	ds_bpermute_b32 v207, v226, v207
	v_mul_f32_e32 v180, 0xbfb8aa3b, v44
	v_exp_f32_e32 v180, v180
	v_mul_f32_e32 v227, 0xbfb8aa3b, v39
	v_exp_f32_e32 v227, v227
	s_waitcnt lgkmcnt(0)
	global_store_dwordx2 v[208:209], v[206:207], off offset:288
	v_mul_f32_e32 v206, 0xbfb8aa3b, v45
	v_mul_f32_e32 v207, 0xbfb8aa3b, v46
	v_mul_f32_e32 v208, 0xbfb8aa3b, v47
	v_exp_f32_e32 v206, v206
	v_exp_f32_e32 v207, v207
	v_exp_f32_e32 v208, v208
	v_add_f32_e32 v180, 1.0, v180
	v_add_f32_e32 v206, 1.0, v206
	v_add_f32_e32 v207, 1.0, v207
	v_add_f32_e32 v208, 1.0, v208
	v_rcp_f32_e32 v180, v180
	v_rcp_f32_e32 v206, v206
	v_rcp_f32_e32 v207, v207
	v_rcp_f32_e32 v208, v208
	v_add_f32_e32 v227, 1.0, v227
	v_cvt_pk_bf16_f32 v180, v180, v206
	ds_bpermute_b32 v206, v226, v180
	v_cvt_pk_bf16_f32 v207, v207, v208
	ds_bpermute_b32 v207, v226, v207
	v_lshl_add_u64 v[208:209], v[130:131], 0, s[4:5]
	s_mov_b32 s4, 0x90000
	v_add_co_u32_e32 v228, vcc, s4, v130
	v_mul_f32_e32 v180, 0xbfb8aa3b, v36
	s_nop 0
	v_addc_co_u32_e32 v229, vcc, 0, v131, vcc
	s_waitcnt lgkmcnt(0)
	global_store_dwordx2 v[228:229], v[206:207], off
	v_mul_f32_e32 v206, 0xbfb8aa3b, v37
	v_mul_f32_e32 v207, 0xbfb8aa3b, v38
	v_exp_f32_e32 v180, v180
	v_exp_f32_e32 v206, v206
	v_exp_f32_e32 v207, v207
	v_rcp_f32_e32 v227, v227
	v_add_f32_e32 v180, 1.0, v180
	v_add_f32_e32 v206, 1.0, v206
	v_add_f32_e32 v207, 1.0, v207
	v_rcp_f32_e32 v180, v180
	v_rcp_f32_e32 v206, v206
	v_rcp_f32_e32 v207, v207
	s_mov_b64 s[4:5], 0xa0000
	v_cvt_pk_bf16_f32 v180, v180, v206
	v_cvt_pk_bf16_f32 v207, v207, v227
	ds_bpermute_b32 v206, v226, v180
	ds_bpermute_b32 v207, v226, v207
	v_exp_f32_e32 v180, v136
	v_exp_f32_e32 v227, v132
	s_waitcnt lgkmcnt(0)
	global_store_dwordx2 v[208:209], v[206:207], off offset:32
	v_exp_f32_e32 v206, v135
	v_exp_f32_e32 v207, v134
	v_add_f32_e32 v180, 1.0, v180
	v_add_f32_e32 v227, 1.0, v227
	v_add_f32_e32 v206, 1.0, v206
	v_add_f32_e32 v207, 1.0, v207
	v_rcp_f32_e32 v180, v180
	v_rcp_f32_e32 v206, v206
	v_rcp_f32_e32 v207, v207
	v_rcp_f32_e32 v227, v227
	v_cvt_pk_bf16_f32 v180, v180, v206
	ds_bpermute_b32 v206, v226, v180
	v_cvt_pk_bf16_f32 v207, v207, v227
	ds_bpermute_b32 v207, v226, v207
	v_mul_f32_e32 v180, 0xbfb8aa3b, v32
	v_mul_f32_e32 v227, 0xbfb8aa3b, v35
	v_exp_f32_e32 v180, v180
	v_exp_f32_e32 v227, v227
	s_waitcnt lgkmcnt(0)
	global_store_dwordx2 v[208:209], v[206:207], off offset:256
	v_mul_f32_e32 v206, 0xbfb8aa3b, v33
	v_mul_f32_e32 v207, 0xbfb8aa3b, v34
	v_exp_f32_e32 v206, v206
	v_exp_f32_e32 v207, v207
	v_add_f32_e32 v180, 1.0, v180
	v_add_f32_e32 v227, 1.0, v227
	v_add_f32_e32 v206, 1.0, v206
	v_add_f32_e32 v207, 1.0, v207
	v_rcp_f32_e32 v180, v180
	v_rcp_f32_e32 v206, v206
	v_rcp_f32_e32 v207, v207
	v_rcp_f32_e32 v227, v227
	v_cvt_pk_bf16_f32 v180, v180, v206
	ds_bpermute_b32 v206, v226, v180
	v_cvt_pk_bf16_f32 v207, v207, v227
	ds_bpermute_b32 v207, v226, v207
	v_mul_f32_e32 v180, 0xbfb8aa3b, v28
	v_exp_f32_e32 v180, v180
	v_mul_f32_e32 v227, 0xbfb8aa3b, v23
	v_exp_f32_e32 v227, v227
	s_waitcnt lgkmcnt(0)
	global_store_dwordx2 v[208:209], v[206:207], off offset:288
	v_mul_f32_e32 v206, 0xbfb8aa3b, v29
	v_mul_f32_e32 v207, 0xbfb8aa3b, v30
	v_mul_f32_e32 v208, 0xbfb8aa3b, v31
	v_exp_f32_e32 v206, v206
	v_exp_f32_e32 v207, v207
	v_exp_f32_e32 v208, v208
	v_add_f32_e32 v180, 1.0, v180
	v_add_f32_e32 v206, 1.0, v206
	v_add_f32_e32 v207, 1.0, v207
	v_add_f32_e32 v208, 1.0, v208
	v_rcp_f32_e32 v180, v180
	v_rcp_f32_e32 v206, v206
	v_rcp_f32_e32 v207, v207
	v_rcp_f32_e32 v208, v208
	v_add_f32_e32 v227, 1.0, v227
	v_cvt_pk_bf16_f32 v180, v180, v206
	ds_bpermute_b32 v206, v226, v180
	v_cvt_pk_bf16_f32 v207, v207, v208
	ds_bpermute_b32 v207, v226, v207
	v_lshl_add_u64 v[208:209], v[130:131], 0, s[4:5]
	s_mov_b32 s4, 0xa0000
	v_add_co_u32_e32 v228, vcc, s4, v130
	v_mul_f32_e32 v180, 0xbfb8aa3b, v20
	s_nop 0
	v_addc_co_u32_e32 v229, vcc, 0, v131, vcc
	s_waitcnt lgkmcnt(0)
	global_store_dwordx2 v[228:229], v[206:207], off
	v_mul_f32_e32 v206, 0xbfb8aa3b, v21
	v_mul_f32_e32 v207, 0xbfb8aa3b, v22
	v_exp_f32_e32 v180, v180
	v_exp_f32_e32 v206, v206
	v_exp_f32_e32 v207, v207
	v_rcp_f32_e32 v227, v227
	v_add_f32_e32 v180, 1.0, v180
	v_add_f32_e32 v206, 1.0, v206
	v_add_f32_e32 v207, 1.0, v207
	v_rcp_f32_e32 v180, v180
	v_rcp_f32_e32 v206, v206
	v_rcp_f32_e32 v207, v207
	s_mov_b64 s[4:5], 0xb0000
	v_cvt_pk_bf16_f32 v180, v180, v206
	v_cvt_pk_bf16_f32 v207, v207, v227
	ds_bpermute_b32 v206, v226, v180
	ds_bpermute_b32 v207, v226, v207
	v_mul_f32_e32 v180, 0xbfb8aa3b, v24
	v_mul_f32_e32 v227, 0xbfb8aa3b, v27
	v_exp_f32_e32 v180, v180
	v_exp_f32_e32 v227, v227
	s_waitcnt lgkmcnt(0)
	global_store_dwordx2 v[208:209], v[206:207], off offset:32
	v_mul_f32_e32 v206, 0xbfb8aa3b, v25
	v_mul_f32_e32 v207, 0xbfb8aa3b, v26
	v_exp_f32_e32 v206, v206
	v_exp_f32_e32 v207, v207
	v_add_f32_e32 v180, 1.0, v180
	v_add_f32_e32 v227, 1.0, v227
	v_add_f32_e32 v206, 1.0, v206
	v_add_f32_e32 v207, 1.0, v207
	v_rcp_f32_e32 v180, v180
	v_rcp_f32_e32 v206, v206
	v_rcp_f32_e32 v207, v207
	v_rcp_f32_e32 v227, v227
	v_cvt_pk_bf16_f32 v180, v180, v206
	ds_bpermute_b32 v206, v226, v180
	v_cvt_pk_bf16_f32 v207, v207, v227
	ds_bpermute_b32 v207, v226, v207
	v_mul_f32_e32 v180, 0xbfb8aa3b, v16
	v_mul_f32_e32 v227, 0xbfb8aa3b, v19
	v_exp_f32_e32 v180, v180
	v_exp_f32_e32 v227, v227
	s_waitcnt lgkmcnt(0)
	global_store_dwordx2 v[208:209], v[206:207], off offset:256
	v_mul_f32_e32 v206, 0xbfb8aa3b, v17
	v_mul_f32_e32 v207, 0xbfb8aa3b, v18
	v_exp_f32_e32 v206, v206
	v_exp_f32_e32 v207, v207
	v_add_f32_e32 v180, 1.0, v180
	v_add_f32_e32 v227, 1.0, v227
	v_add_f32_e32 v206, 1.0, v206
	v_add_f32_e32 v207, 1.0, v207
	v_rcp_f32_e32 v180, v180
	v_rcp_f32_e32 v206, v206
	v_rcp_f32_e32 v207, v207
	v_rcp_f32_e32 v227, v227
	v_cvt_pk_bf16_f32 v180, v180, v206
	ds_bpermute_b32 v206, v226, v180
	v_cvt_pk_bf16_f32 v207, v207, v227
	ds_bpermute_b32 v207, v226, v207
	v_mul_f32_e32 v180, 0xbfb8aa3b, v12
	v_exp_f32_e32 v180, v180
	s_waitcnt lgkmcnt(0)
	global_store_dwordx2 v[208:209], v[206:207], off offset:288
	v_mul_f32_e32 v206, 0xbfb8aa3b, v13
	v_mul_f32_e32 v207, 0xbfb8aa3b, v14
	v_mul_f32_e32 v208, 0xbfb8aa3b, v15
	v_exp_f32_e32 v206, v206
	v_exp_f32_e32 v207, v207
	v_exp_f32_e32 v208, v208
	v_add_f32_e32 v180, 1.0, v180
	v_add_f32_e32 v206, 1.0, v206
	v_add_f32_e32 v207, 1.0, v207
	v_add_f32_e32 v208, 1.0, v208
	v_rcp_f32_e32 v180, v180
	v_rcp_f32_e32 v206, v206
	v_rcp_f32_e32 v207, v207
	v_rcp_f32_e32 v208, v208
	v_cvt_pk_bf16_f32 v180, v180, v206
	ds_bpermute_b32 v206, v226, v180
	v_cvt_pk_bf16_f32 v207, v207, v208
	ds_bpermute_b32 v207, v226, v207
	v_lshl_add_u64 v[208:209], v[130:131], 0, s[4:5]
	s_mov_b32 s4, 0xb0000
	v_add_co_u32_e32 v130, vcc, s4, v130
	v_mul_f32_e32 v180, 0xbfb8aa3b, v6
	s_nop 0
	v_addc_co_u32_e32 v131, vcc, 0, v131, vcc
	s_waitcnt lgkmcnt(0)
	global_store_dwordx2 v[130:131], v[206:207], off
	v_mul_f32_e32 v130, 0xbfb8aa3b, v4
	v_mul_f32_e32 v131, 0xbfb8aa3b, v5
	v_mul_f32_e32 v206, 0xbfb8aa3b, v7
	v_exp_f32_e32 v130, v130
	v_exp_f32_e32 v131, v131
	v_exp_f32_e32 v180, v180
	v_exp_f32_e32 v206, v206
	v_add_f32_e32 v130, 1.0, v130
	v_add_f32_e32 v131, 1.0, v131
	v_add_f32_e32 v180, 1.0, v180
	v_add_f32_e32 v206, 1.0, v206
	v_rcp_f32_e32 v130, v130
	v_rcp_f32_e32 v131, v131
	v_rcp_f32_e32 v180, v180
	v_rcp_f32_e32 v206, v206
	s_mov_b64 s[4:5], 0
	v_cvt_pk_bf16_f32 v130, v130, v131
	ds_bpermute_b32 v130, v226, v130
	v_cvt_pk_bf16_f32 v131, v180, v206
	ds_bpermute_b32 v131, v226, v131
	v_mul_f32_e32 v180, 0xbfb8aa3b, v10
	v_mul_f32_e32 v206, 0xbfb8aa3b, v11
	v_exp_f32_e32 v180, v180
	v_exp_f32_e32 v206, v206
	s_waitcnt lgkmcnt(0)
	global_store_dwordx2 v[208:209], v[130:131], off offset:32
	v_mul_f32_e32 v130, 0xbfb8aa3b, v8
	v_mul_f32_e32 v131, 0xbfb8aa3b, v9
	v_exp_f32_e32 v130, v130
	v_exp_f32_e32 v131, v131
	v_add_f32_e32 v180, 1.0, v180
	v_add_f32_e32 v206, 1.0, v206
	v_add_f32_e32 v130, 1.0, v130
	v_add_f32_e32 v131, 1.0, v131
	v_rcp_f32_e32 v130, v130
	v_rcp_f32_e32 v131, v131
	v_rcp_f32_e32 v180, v180
	v_rcp_f32_e32 v206, v206
	v_cvt_pk_bf16_f32 v130, v130, v131
	ds_bpermute_b32 v130, v226, v130
	v_cvt_pk_bf16_f32 v131, v180, v206
	ds_bpermute_b32 v131, v226, v131
	v_mul_f32_e32 v180, 0xbfb8aa3b, v2
	v_mul_f32_e32 v206, 0xbfb8aa3b, v3
	v_exp_f32_e32 v180, v180
	v_exp_f32_e32 v206, v206
	s_waitcnt lgkmcnt(0)
	global_store_dwordx2 v[208:209], v[130:131], off offset:256
	v_mul_f32_e32 v130, 0xbfb8aa3b, v0
	v_mul_f32_e32 v131, 0xbfb8aa3b, v1
	v_exp_f32_e32 v130, v130
	v_exp_f32_e32 v131, v131
	v_add_f32_e32 v180, 1.0, v180
	v_add_f32_e32 v206, 1.0, v206
	v_add_f32_e32 v130, 1.0, v130
	v_add_f32_e32 v131, 1.0, v131
	v_rcp_f32_e32 v130, v130
	v_rcp_f32_e32 v131, v131
	v_rcp_f32_e32 v180, v180
	v_rcp_f32_e32 v206, v206
	v_cvt_pk_bf16_f32 v130, v130, v131
	ds_bpermute_b32 v130, v226, v130
	v_cvt_pk_bf16_f32 v131, v180, v206
	ds_bpermute_b32 v131, v226, v131
	s_waitcnt lgkmcnt(0)
	global_store_dwordx2 v[208:209], v[130:131], off offset:288

.LBB0_1024:
	s_waitcnt lgkmcnt(0)
	ds_read_b128 v[128:131], v179
	ds_read_b128 v[132:135], v179 offset:1024
	ds_read_b128 v[136:139], v179 offset:2048
	ds_read_b128 v[140:143], v179 offset:3072
	s_add_i32 s62, s36, 2
	s_add_u32 s37, s4, 0xfff80080
	s_addc_u32 s38, s5, -1
	s_cmp_eq_u32 s59, s36
	s_cselect_b32 s36, s58, s60
	s_cselect_b32 s39, s21, s38
	s_cselect_b32 s38, s25, s37
	s_cselect_b32 s37, s23, s61

	s_add_i32 m0, s31, 0xc000
	ds_read_b128 v[144:147], v190
	ds_read_b128 v[148:151], v190 offset:1024
	ds_read_b128 v[152:155], v190 offset:2048
	ds_read_b128 v[156:159], v190 offset:3072
	ds_read_b128 v[180:183], v190 offset:4096
	ds_read_b128 v[184:187], v190 offset:5120
	ds_read_b128 v[194:197], v190 offset:6144
	ds_read_b128 v[198:201], v190 offset:7168
	global_load_lds_dwordx4 v162, s[4:5]
	s_add_i32 m0, s31, 0xe000
	s_nop 0

	global_load_lds_dwordx4 v164, s[4:5]
	s_waitcnt lgkmcnt(8)
	s_barrier
	s_waitcnt lgkmcnt(0)


	v_mfma_f32_16x16x32_bf16 v[124:127], v[128:131], v[144:147], v[124:127]
	v_mfma_f32_16x16x32_bf16 v[120:123], v[136:139], v[144:147], v[120:123]
	v_mfma_f32_16x16x32_bf16 v[116:119], v[128:131], v[152:155], v[116:119]
	v_mfma_f32_16x16x32_bf16 v[104:107], v[136:139], v[152:155], v[104:107]
	v_mfma_f32_16x16x32_bf16 v[96:99], v[128:131], v[180:183], v[96:99]
	v_mfma_f32_16x16x32_bf16 v[88:91], v[136:139], v[180:183], v[88:91]
	v_mfma_f32_16x16x32_bf16 v[80:83], v[128:131], v[194:197], v[80:83]
	v_mfma_f32_16x16x32_bf16 v[72:75], v[136:139], v[194:197], v[72:75]
	v_mfma_f32_16x16x32_bf16 v[124:127], v[132:135], v[148:151], v[124:127]
	v_mfma_f32_16x16x32_bf16 v[120:123], v[140:143], v[148:151], v[120:123]
	v_mfma_f32_16x16x32_bf16 v[116:119], v[132:135], v[156:159], v[116:119]
	v_mfma_f32_16x16x32_bf16 v[104:107], v[140:143], v[156:159], v[104:107]
	v_mfma_f32_16x16x32_bf16 v[96:99], v[132:135], v[184:187], v[96:99]
	v_mfma_f32_16x16x32_bf16 v[88:91], v[140:143], v[184:187], v[88:91]
	v_mfma_f32_16x16x32_bf16 v[80:83], v[132:135], v[198:201], v[80:83]
	v_mfma_f32_16x16x32_bf16 v[72:75], v[140:143], v[198:201], v[72:75]

	s_barrier
	s_add_i32 s63, s52, s42
	v_lshl_add_u64 v[166:167], s[36:37], 0, v[172:173]
	s_mov_b32 m0, s63
	ds_read_b128 v[202:205], v191
	ds_read_b128 v[206:209], v191 offset:1024
	ds_read_b128 v[222:225], v191 offset:2048
	ds_read_b128 v[226:229], v191 offset:3072
	global_load_lds_dwordx4 v[166:167], off
	s_add_i32 m0, s63, 0x2000
	v_lshl_add_u64 v[188:189], s[36:37], 0, v[174:175]

	global_load_lds_dwordx4 v[188:189], off
	s_barrier
	s_waitcnt lgkmcnt(0)


	v_mfma_f32_16x16x32_bf16 v[112:115], v[202:205], v[144:147], v[112:115]
	v_mfma_f32_16x16x32_bf16 v[108:111], v[222:225], v[144:147], v[108:111]
	v_mfma_f32_16x16x32_bf16 v[100:103], v[202:205], v[152:155], v[100:103]
	v_mfma_f32_16x16x32_bf16 v[92:95], v[222:225], v[152:155], v[92:95]
	v_mfma_f32_16x16x32_bf16 v[84:87], v[202:205], v[180:183], v[84:87]
	v_mfma_f32_16x16x32_bf16 v[76:79], v[222:225], v[180:183], v[76:79]
	v_mfma_f32_16x16x32_bf16 v[68:71], v[202:205], v[194:197], v[68:71]
	v_mfma_f32_16x16x32_bf16 v[64:67], v[222:225], v[194:197], v[64:67]
	v_mfma_f32_16x16x32_bf16 v[112:115], v[206:209], v[148:151], v[112:115]
	v_mfma_f32_16x16x32_bf16 v[108:111], v[226:229], v[148:151], v[108:111]
	v_mfma_f32_16x16x32_bf16 v[100:103], v[206:209], v[156:159], v[100:103]
	v_mfma_f32_16x16x32_bf16 v[92:95], v[226:229], v[156:159], v[92:95]
	v_mfma_f32_16x16x32_bf16 v[84:87], v[206:209], v[184:187], v[84:87]
	v_mfma_f32_16x16x32_bf16 v[76:79], v[226:229], v[184:187], v[76:79]
	v_mfma_f32_16x16x32_bf16 v[68:71], v[206:209], v[198:201], v[68:71]
	v_mfma_f32_16x16x32_bf16 v[64:67], v[226:229], v[198:201], v[64:67]

	s_mov_b32 m0, s31
	v_lshl_add_u64 v[230:231], s[38:39], 0, v[172:173]
	s_barrier
	ds_read_b128 v[144:147], v190 offset:16384
	ds_read_b128 v[148:151], v190 offset:17408
	ds_read_b128 v[152:155], v190 offset:18432
	ds_read_b128 v[156:159], v190 offset:19456
	ds_read_b128 v[180:183], v190 offset:20480
	ds_read_b128 v[184:187], v190 offset:21504
	ds_read_b128 v[194:197], v190 offset:22528
	ds_read_b128 v[198:201], v190 offset:23552
	global_load_lds_dwordx4 v[230:231], off
	s_mov_b32 m0, s35
	v_lshl_add_u64 v[232:233], s[38:39], 0, v[174:175]

	global_load_lds_dwordx4 v[232:233], off
	s_barrier
	s_waitcnt lgkmcnt(0)


	v_mfma_f32_16x16x32_bf16 v[60:63], v[128:131], v[144:147], v[60:63]
	v_mfma_f32_16x16x32_bf16 v[56:59], v[136:139], v[144:147], v[56:59]
	v_mfma_f32_16x16x32_bf16 v[52:55], v[128:131], v[152:155], v[52:55]
	v_mfma_f32_16x16x32_bf16 v[40:43], v[136:139], v[152:155], v[40:43]
	v_mfma_f32_16x16x32_bf16 v[36:39], v[128:131], v[180:183], v[36:39]
	v_mfma_f32_16x16x32_bf16 v[24:27], v[136:139], v[180:183], v[24:27]
	v_mfma_f32_16x16x32_bf16 v[20:23], v[128:131], v[194:197], v[20:23]
	v_mfma_f32_16x16x32_bf16 v[8:11], v[136:139], v[194:197], v[8:11]
	v_mfma_f32_16x16x32_bf16 v[60:63], v[132:135], v[148:151], v[60:63]
	v_mfma_f32_16x16x32_bf16 v[56:59], v[140:143], v[148:151], v[56:59]
	v_mfma_f32_16x16x32_bf16 v[52:55], v[132:135], v[156:159], v[52:55]
	v_mfma_f32_16x16x32_bf16 v[40:43], v[140:143], v[156:159], v[40:43]
	v_mfma_f32_16x16x32_bf16 v[36:39], v[132:135], v[184:187], v[36:39]
	v_mfma_f32_16x16x32_bf16 v[24:27], v[140:143], v[184:187], v[24:27]
	v_mfma_f32_16x16x32_bf16 v[20:23], v[132:135], v[198:201], v[20:23]
	v_mfma_f32_16x16x32_bf16 v[8:11], v[140:143], v[198:201], v[8:11]

	s_barrier
	s_add_u32 s64, s36, 0x80000
	s_addc_u32 s65, s37, 0
	s_add_i32 s63, s53, s42
	s_mov_b32 m0, s63
	s_nop 0

	global_load_lds_dwordx4 v172, s[64:65]
	s_add_i32 m0, s63, 0x2000
	s_nop 0

	global_load_lds_dwordx4 v174, s[64:65]
	s_waitcnt vmcnt(6)
	s_barrier

	v_mfma_f32_16x16x32_bf16 v[48:51], v[202:205], v[144:147], v[48:51]
	v_mfma_f32_16x16x32_bf16 v[44:47], v[222:225], v[144:147], v[44:47]
	v_mfma_f32_16x16x32_bf16 v[32:35], v[202:205], v[152:155], v[32:35]
	v_mfma_f32_16x16x32_bf16 v[28:31], v[222:225], v[152:155], v[28:31]
	v_mfma_f32_16x16x32_bf16 v[16:19], v[202:205], v[180:183], v[16:19]
	v_mfma_f32_16x16x32_bf16 v[12:15], v[222:225], v[180:183], v[12:15]
	v_mfma_f32_16x16x32_bf16 v[4:7], v[202:205], v[194:197], v[4:7]
	v_mfma_f32_16x16x32_bf16 v[0:3], v[222:225], v[194:197], v[0:3]
	v_mfma_f32_16x16x32_bf16 v[48:51], v[206:209], v[148:151], v[48:51]
	v_mfma_f32_16x16x32_bf16 v[44:47], v[226:229], v[148:151], v[44:47]
	v_mfma_f32_16x16x32_bf16 v[32:35], v[206:209], v[156:159], v[32:35]
	v_mfma_f32_16x16x32_bf16 v[28:31], v[226:229], v[156:159], v[28:31]
	v_mfma_f32_16x16x32_bf16 v[16:19], v[206:209], v[184:187], v[16:19]
	v_mfma_f32_16x16x32_bf16 v[12:15], v[226:229], v[184:187], v[12:15]
	v_mfma_f32_16x16x32_bf16 v[4:7], v[206:209], v[198:201], v[4:7]
	v_mfma_f32_16x16x32_bf16 v[0:3], v[226:229], v[198:201], v[0:3]

	s_add_i32 s63, 0, 0x18000
	v_add_u32_e32 v140, s63, v177
	s_barrier
	ds_read_b128 v[128:131], v140
	ds_read_b128 v[132:135], v140 offset:1024
	ds_read_b128 v[136:139], v140 offset:2048
	ds_read_b128 v[140:143], v140 offset:3072
	s_add_u32 s38, s38, 0x80000
	s_addc_u32 s39, s39, 0
	s_mov_b32 m0, s43

	ds_read_b128 v[144:147], v190 offset:32768
	ds_read_b128 v[148:151], v190 offset:33792
	ds_read_b128 v[152:155], v190 offset:34816
	ds_read_b128 v[156:159], v190 offset:35840
	ds_read_b128 v[180:183], v190 offset:36864
	ds_read_b128 v[184:187], v190 offset:37888
	ds_read_b128 v[194:197], v190 offset:38912
	ds_read_b128 v[198:201], v190 offset:39936
	global_load_lds_dwordx4 v172, s[38:39]
	s_mov_b32 m0, s44
	s_nop 0

	global_load_lds_dwordx4 v174, s[38:39]
	s_waitcnt lgkmcnt(8)
	s_barrier
	s_waitcnt lgkmcnt(0)


	v_mfma_f32_16x16x32_bf16 v[124:127], v[128:131], v[144:147], v[124:127]
	v_mfma_f32_16x16x32_bf16 v[120:123], v[136:139], v[144:147], v[120:123]
	v_mfma_f32_16x16x32_bf16 v[116:119], v[128:131], v[152:155], v[116:119]
	v_mfma_f32_16x16x32_bf16 v[104:107], v[136:139], v[152:155], v[104:107]
	v_mfma_f32_16x16x32_bf16 v[96:99], v[128:131], v[180:183], v[96:99]
	v_mfma_f32_16x16x32_bf16 v[88:91], v[136:139], v[180:183], v[88:91]
	v_mfma_f32_16x16x32_bf16 v[80:83], v[128:131], v[194:197], v[80:83]
	v_mfma_f32_16x16x32_bf16 v[72:75], v[136:139], v[194:197], v[72:75]
	v_mfma_f32_16x16x32_bf16 v[124:127], v[132:135], v[148:151], v[124:127]
	v_mfma_f32_16x16x32_bf16 v[120:123], v[140:143], v[148:151], v[120:123]
	v_mfma_f32_16x16x32_bf16 v[116:119], v[132:135], v[156:159], v[116:119]
	v_mfma_f32_16x16x32_bf16 v[104:107], v[140:143], v[156:159], v[104:107]
	v_mfma_f32_16x16x32_bf16 v[96:99], v[132:135], v[184:187], v[96:99]
	v_mfma_f32_16x16x32_bf16 v[88:91], v[140:143], v[184:187], v[88:91]
	v_mfma_f32_16x16x32_bf16 v[80:83], v[132:135], v[198:201], v[80:83]
	v_mfma_f32_16x16x32_bf16 v[72:75], v[140:143], v[198:201], v[72:75]

	s_barrier
	s_add_i32 s38, 0, 0x1c000
	s_add_i32 s39, s63, s42
	v_add_u32_e32 v160, s38, v177
	v_lshl_add_u64 v[166:167], v[166:167], 0, s[14:15]
	s_mov_b32 m0, s39
	ds_read_b128 v[202:205], v160
	ds_read_b128 v[206:209], v160 offset:1024
	ds_read_b128 v[222:225], v160 offset:2048
	ds_read_b128 v[226:229], v160 offset:3072
	global_load_lds_dwordx4 v[166:167], off
	s_add_i32 m0, s39, 0x2000
	v_lshl_add_u64 v[166:167], v[188:189], 0, s[14:15]

	global_load_lds_dwordx4 v[166:167], off
	s_barrier
	s_waitcnt lgkmcnt(0)


	v_mfma_f32_16x16x32_bf16 v[112:115], v[202:205], v[144:147], v[112:115]
	v_mfma_f32_16x16x32_bf16 v[108:111], v[222:225], v[144:147], v[108:111]
	v_mfma_f32_16x16x32_bf16 v[100:103], v[202:205], v[152:155], v[100:103]
	v_mfma_f32_16x16x32_bf16 v[92:95], v[222:225], v[152:155], v[92:95]
	v_mfma_f32_16x16x32_bf16 v[84:87], v[202:205], v[180:183], v[84:87]
	v_mfma_f32_16x16x32_bf16 v[76:79], v[222:225], v[180:183], v[76:79]
	v_mfma_f32_16x16x32_bf16 v[68:71], v[202:205], v[194:197], v[68:71]
	v_mfma_f32_16x16x32_bf16 v[64:67], v[222:225], v[194:197], v[64:67]
	v_mfma_f32_16x16x32_bf16 v[112:115], v[206:209], v[148:151], v[112:115]
	v_mfma_f32_16x16x32_bf16 v[108:111], v[226:229], v[148:151], v[108:111]
	v_mfma_f32_16x16x32_bf16 v[100:103], v[206:209], v[156:159], v[100:103]
	v_mfma_f32_16x16x32_bf16 v[92:95], v[226:229], v[156:159], v[92:95]
	v_mfma_f32_16x16x32_bf16 v[84:87], v[206:209], v[184:187], v[84:87]
	v_mfma_f32_16x16x32_bf16 v[76:79], v[226:229], v[184:187], v[76:79]
	v_mfma_f32_16x16x32_bf16 v[68:71], v[206:209], v[198:201], v[68:71]
	v_mfma_f32_16x16x32_bf16 v[64:67], v[226:229], v[198:201], v[64:67]

	s_mov_b32 m0, s48
	v_lshl_add_u64 v[166:167], v[230:231], 0, s[14:15]
	s_barrier
	ds_read_b128 v[144:147], v190 offset:49152
	ds_read_b128 v[148:151], v190 offset:50176
	ds_read_b128 v[152:155], v190 offset:51200
	ds_read_b128 v[156:159], v190 offset:52224
	ds_read_b128 v[180:183], v190 offset:53248
	ds_read_b128 v[184:187], v190 offset:54272
	ds_read_b128 v[194:197], v190 offset:55296
	ds_read_b128 v[198:201], v190 offset:56320
	global_load_lds_dwordx4 v[166:167], off
	s_mov_b32 m0, s49
	v_lshl_add_u64 v[166:167], v[232:233], 0, s[14:15]

	global_load_lds_dwordx4 v[166:167], off
	s_barrier
	s_waitcnt lgkmcnt(0)


	v_mfma_f32_16x16x32_bf16 v[60:63], v[128:131], v[144:147], v[60:63]
	v_mfma_f32_16x16x32_bf16 v[56:59], v[136:139], v[144:147], v[56:59]
	v_mfma_f32_16x16x32_bf16 v[52:55], v[128:131], v[152:155], v[52:55]
	v_mfma_f32_16x16x32_bf16 v[40:43], v[136:139], v[152:155], v[40:43]
	v_mfma_f32_16x16x32_bf16 v[36:39], v[128:131], v[180:183], v[36:39]
	v_mfma_f32_16x16x32_bf16 v[24:27], v[136:139], v[180:183], v[24:27]
	v_mfma_f32_16x16x32_bf16 v[20:23], v[128:131], v[194:197], v[20:23]
	v_mfma_f32_16x16x32_bf16 v[8:11], v[136:139], v[194:197], v[8:11]
	v_mfma_f32_16x16x32_bf16 v[60:63], v[132:135], v[148:151], v[60:63]
	v_mfma_f32_16x16x32_bf16 v[56:59], v[140:143], v[148:151], v[56:59]
	v_mfma_f32_16x16x32_bf16 v[52:55], v[132:135], v[156:159], v[52:55]
	v_mfma_f32_16x16x32_bf16 v[40:43], v[140:143], v[156:159], v[40:43]
	v_mfma_f32_16x16x32_bf16 v[36:39], v[132:135], v[184:187], v[36:39]
	v_mfma_f32_16x16x32_bf16 v[24:27], v[140:143], v[184:187], v[24:27]
	v_mfma_f32_16x16x32_bf16 v[20:23], v[132:135], v[198:201], v[20:23]
	v_mfma_f32_16x16x32_bf16 v[8:11], v[140:143], v[198:201], v[8:11]

	s_barrier
	s_add_u32 s36, s36, 0x80080
	s_addc_u32 s37, s37, 0
	s_add_i32 s38, s38, s42
	s_mov_b32 m0, s38
	s_nop 0

	global_load_lds_dwordx4 v172, s[36:37]
	s_add_i32 m0, s38, 0x2000
	s_nop 0

	global_load_lds_dwordx4 v174, s[36:37]
	s_waitcnt vmcnt(6)
	s_barrier

	v_mfma_f32_16x16x32_bf16 v[48:51], v[202:205], v[144:147], v[48:51]
	v_mfma_f32_16x16x32_bf16 v[44:47], v[222:225], v[144:147], v[44:47]
	v_mfma_f32_16x16x32_bf16 v[32:35], v[202:205], v[152:155], v[32:35]
	v_mfma_f32_16x16x32_bf16 v[28:31], v[222:225], v[152:155], v[28:31]
	v_mfma_f32_16x16x32_bf16 v[16:19], v[202:205], v[180:183], v[16:19]
	v_mfma_f32_16x16x32_bf16 v[12:15], v[222:225], v[180:183], v[12:15]
	v_mfma_f32_16x16x32_bf16 v[4:7], v[202:205], v[194:197], v[4:7]
	v_mfma_f32_16x16x32_bf16 v[0:3], v[222:225], v[194:197], v[0:3]
	v_mfma_f32_16x16x32_bf16 v[48:51], v[206:209], v[148:151], v[48:51]
	v_mfma_f32_16x16x32_bf16 v[44:47], v[226:229], v[148:151], v[44:47]
	v_mfma_f32_16x16x32_bf16 v[32:35], v[206:209], v[156:159], v[32:35]
	v_mfma_f32_16x16x32_bf16 v[28:31], v[226:229], v[156:159], v[28:31]
	v_mfma_f32_16x16x32_bf16 v[16:19], v[206:209], v[184:187], v[16:19]
	v_mfma_f32_16x16x32_bf16 v[12:15], v[226:229], v[184:187], v[12:15]
	v_mfma_f32_16x16x32_bf16 v[4:7], v[206:209], v[198:201], v[4:7]
	v_mfma_f32_16x16x32_bf16 v[0:3], v[226:229], v[198:201], v[0:3]

	s_add_u32 s4, s4, 0x100
	s_addc_u32 s5, s5, 0
	s_add_u32 s60, s60, 0x100
	s_addc_u32 s61, s61, 0
	s_cmp_ge_i32 s62, s17
	s_mov_b32 s36, s62
	s_barrier
	s_cbranch_scc0 .LBB0_1024
	v_mov_b32_e32 v128, v210
	v_mov_b32_e32 v129, v169
	s_cmp_lt_i32 s12, 0
	v_lshl_add_u32 v128, v128, 4, v129
	v_ashrrev_i32_e32 v166, 2, v128
	v_and_b32_e32 v160, 3, v129
	v_and_b32_e32 v128, -4, v128
	v_lshl_add_u32 v193, v160, 6, v128
	s_mov_b64 s[4:5], -1
	s_cbranch_scc0 .LBB0_1043
	s_lshl_b32 s4, s30, 8
	v_lshl_or_b32 v128, v160, 2, s4
	s_lshl_b32 s4, s34, 8
	v_or_b32_e32 v180, s47, v128
	s_add_i32 s4, s4, s46
	v_readlane_b32 s60, v254, 6
	v_ashrrev_i32_e32 v181, 31, v180
	v_add_u32_e32 v184, s4, v166
	s_cmp_lt_i32 s34, 32
	v_readlane_b32 s61, v254, 7
	v_lshlrev_b64 v[128:129], 2, v[180:181]
	v_readlane_b32 s62, v254, 8
	v_readlane_b32 s63, v254, 9
	v_readlane_b32 s64, v254, 10
	v_readlane_b32 s65, v254, 11
	v_readlane_b32 s66, v254, 12
	v_readlane_b32 s67, v254, 13
	v_readlane_b32 s68, v254, 14
	v_readlane_b32 s69, v254, 15
	v_readlane_b32 s70, v254, 16
	v_readlane_b32 s71, v254, 17
	v_readlane_b32 s72, v254, 18
	v_readlane_b32 s73, v254, 19
	v_readlane_b32 s74, v254, 20
	v_readlane_b32 s75, v254, 21
	s_cselect_b32 s5, s61, s51
	s_cselect_b32 s4, s60, s50
	v_ashrrev_i32_e32 v185, 31, v184
	v_lshl_add_u64 v[182:183], s[4:5], 0, v[128:129]
	v_lshlrev_b64 v[130:131], 13, v[184:185]
	v_readlane_b32 s60, v254, 22
	v_lshl_add_u64 v[136:137], v[182:183], 0, v[130:131]
	v_readlane_b32 s61, v254, 23
	v_readlane_b32 s68, v254, 30
	v_readlane_b32 s69, v254, 31
	global_load_dwordx4 v[196:199], v[136:137], off nt
	global_load_dwordx4 v[200:203], v[136:137], off offset:64 nt
	global_load_dwordx4 v[204:207], v[136:137], off offset:512 nt
	s_mov_b64 s[60:61], s[68:69]
	v_lshl_add_u64 v[138:139], s[60:61], 0, v[128:129]
	global_load_dwordx4 v[140:143], v[138:139], off
	global_load_dwordx4 v[132:135], v[138:139], off offset:64
	global_load_dwordx4 v[128:131], v[138:139], off offset:512
	global_load_dwordx4 v[222:225], v[136:137], off offset:576 nt
	v_and_b32_e32 v145, 64, v192
	global_load_dwordx4 v[136:139], v[138:139], off offset:576
	v_xor_b32_e32 v144, 1, v192
	v_add_u32_e32 v194, 64, v145
	v_add_u32_e32 v186, 16, v184
	v_cmp_lt_i32_e64 s[4:5], v144, v194
	v_ashrrev_i32_e32 v187, 31, v186
	ds_bpermute_b32 v188, v193, v124
	v_cndmask_b32_e64 v195, v192, v144, s[4:5]
	v_lshlrev_b64 v[144:145], 13, v[186:187]
	v_lshl_add_u64 v[144:145], v[182:183], 0, v[144:145]
	global_load_dwordx4 v[156:159], v[144:145], off nt
	global_load_dwordx4 v[152:155], v[144:145], off offset:64 nt
	global_load_dwordx4 v[148:151], v[144:145], off offset:512 nt
	s_nop 0
	global_load_dwordx4 v[144:147], v[144:145], off offset:576 nt
	ds_bpermute_b32 v189, v193, v125
	ds_bpermute_b32 v208, v193, v126
	ds_bpermute_b32 v209, v193, v127
	ds_bpermute_b32 v226, v193, v120
	ds_bpermute_b32 v227, v193, v121
	ds_bpermute_b32 v228, v193, v122
	ds_bpermute_b32 v229, v193, v123
	ds_bpermute_b32 v230, v193, v112
	ds_bpermute_b32 v231, v193, v113
	v_readlane_b32 s64, v254, 26
	v_readlane_b32 s65, v254, 27
	v_readlane_b32 s66, v254, 28
	v_readlane_b32 s67, v254, 29
	v_readlane_b32 s72, v254, 34
	v_readlane_b32 s73, v254, 35
	v_readlane_b32 s74, v254, 36
	v_readlane_b32 s75, v254, 37
	s_mov_b64 s[64:65], s[72:73]
	ds_bpermute_b32 v232, v193, v114
	ds_bpermute_b32 v233, v193, v115
	v_lshlrev_b64 v[234:235], 11, v[184:185]
	s_mov_b64 s[66:67], s[74:75]
	v_lshl_add_u64 v[234:235], v[234:235], 0, v[180:181]
	v_xor_b32_e32 v167, 2, v192
	v_lshl_add_u64 v[236:237], v[234:235], 2, s[66:67]
	v_readlane_b32 s2, v254, 54
	v_cmp_lt_i32_e64 s[4:5], v167, v194
	v_lshlrev_b32_e32 v194, 2, v195
	v_lshlrev_b64 v[234:235], 1, v[234:235]
	v_readlane_b32 s3, v254, 55
	v_or_b32_e32 v240, 32, v234
	v_mov_b32_e32 v241, v235
	v_lshl_add_u64 v[238:239], s[2:3], 0, v[234:235]
	v_lshl_add_u64 v[240:241], s[2:3], 0, v[240:241]
	v_cndmask_b32_e64 v167, v192, v167, s[4:5]
	v_lshlrev_b32_e32 v167, 2, v167
	v_cmp_eq_u32_e32 vcc, 0, v160
	v_readlane_b32 s62, v254, 24
	v_readlane_b32 s63, v254, 25
	v_readlane_b32 s70, v254, 32
	v_readlane_b32 s71, v254, 33
	s_waitcnt vmcnt(0) lgkmcnt(0)
	v_pk_add_f32 v[198:199], v[198:199], v[208:209]
	v_pk_add_f32 v[196:197], v[196:197], v[188:189]
	v_pk_add_f32 v[202:203], v[202:203], v[228:229]
	v_pk_add_f32 v[200:201], v[200:201], v[226:227]
	v_pk_add_f32 v[204:205], v[204:205], v[230:231]
	v_mul_f32_e32 v195, v197, v197
	v_mul_f32_e32 v221, v199, v199
	global_store_dwordx4 v[236:237], v[196:199], off
	v_pk_mul_f32 v[188:189], v[142:143], v[198:199]
	v_pk_mul_f32 v[208:209], v[140:141], v[196:197]
	v_mul_f32_e32 v199, v201, v201
	v_mul_f32_e32 v230, v203, v203
	v_pk_mul_f32 v[226:227], v[134:135], v[202:203]
	v_pk_mul_f32 v[228:229], v[132:133], v[200:201]
	v_fmac_f32_e32 v195, v196, v196
	v_fmac_f32_e32 v221, v198, v198
	v_cvt_pk_bf16_f32 v196, v208, v209
	v_cvt_pk_bf16_f32 v197, v188, v189
	v_fmac_f32_e32 v199, v200, v200
	v_fmac_f32_e32 v230, v202, v202
	v_pk_add_f32 v[206:207], v[206:207], v[232:233]
	v_cvt_pk_bf16_f32 v188, v228, v229
	v_cvt_pk_bf16_f32 v189, v226, v227
	v_add_f32_e32 v195, v195, v221
	global_store_dwordx2 v[238:239], v[196:197], off
	v_add_f32_e32 v196, v199, v230
	global_store_dwordx4 v[236:237], v[200:203], off offset:64
	global_store_dwordx2 v[240:241], v[188:189], off
	v_add_f32_e32 v188, v195, v196
	v_mul_f32_e32 v189, v205, v205
	v_mul_f32_e32 v195, v207, v207
	v_fmac_f32_e32 v189, v204, v204
	v_fmac_f32_e32 v195, v206, v206
	ds_bpermute_b32 v200, v193, v108
	ds_bpermute_b32 v198, v193, v110
	ds_bpermute_b32 v199, v193, v111
	ds_bpermute_b32 v201, v193, v109
	v_add_f32_e32 v189, v189, v195
	v_add_f32_e32 v195, v188, v189
	v_pk_mul_f32 v[188:189], v[130:131], v[206:207]
	v_pk_mul_f32 v[196:197], v[128:129], v[204:205]
	global_store_dwordx4 v[236:237], v[204:207], off offset:512
	v_cvt_pk_bf16_f32 v196, v196, v197
	v_cvt_pk_bf16_f32 v197, v188, v189
	v_or_b32_e32 v188, 0x100, v234
	v_mov_b32_e32 v189, v235
	v_lshl_add_u64 v[188:189], s[2:3], 0, v[188:189]
	global_store_dwordx2 v[188:189], v[196:197], off
	s_waitcnt lgkmcnt(1)
	v_pk_add_f32 v[198:199], v[224:225], v[198:199]
	s_waitcnt lgkmcnt(0)
	v_pk_add_f32 v[196:197], v[222:223], v[200:201]
	v_mul_f32_e32 v189, v199, v199
	v_mul_f32_e32 v188, v197, v197
	v_fmac_f32_e32 v188, v196, v196
	v_fmac_f32_e32 v189, v198, v198
	v_add_f32_e32 v188, v188, v189
	v_add_f32_e32 v195, v195, v188
	ds_bpermute_b32 v200, v194, v195
	v_pk_mul_f32 v[188:189], v[136:137], v[196:197]
	global_store_dwordx4 v[236:237], v[196:199], off offset:576
	v_or_b32_e32 v234, 0x120, v234
	s_nop 0
	v_cvt_pk_bf16_f32 v196, v188, v189
	s_waitcnt lgkmcnt(0)
	v_add_f32_e32 v188, v195, v200
	ds_bpermute_b32 v189, v167, v188
	v_pk_mul_f32 v[198:199], v[138:139], v[198:199]
	s_nop 0
	v_cvt_pk_bf16_f32 v197, v198, v199
	v_lshl_add_u64 v[198:199], s[2:3], 0, v[234:235]
	global_store_dwordx2 v[198:199], v[196:197], off
	s_and_saveexec_b64 s[4:5], vcc
	s_cbranch_execz .LBB0_1028
	s_waitcnt lgkmcnt(0)
	v_add_f32_e32 v195, v188, v189
	s_lshl_b32 s36, s30, 2
	v_lshlrev_b64 v[188:189], 7, v[184:185]
	s_ashr_i32 s37, s36, 31
	v_lshl_add_u64 v[188:189], s[10:11], 0, v[188:189]
	v_lshl_add_u64 v[188:189], s[36:37], 2, v[188:189]
	s_lshl_b32 s36, s45, 2
	s_mov_b32 s37, s13
	v_lshl_add_u64 v[188:189], v[188:189], 0, s[36:37]
	global_store_dword v[188:189], v195, off

.LBB0_1167:
	ds_read_b128 v[148:151], v143
	ds_read_b128 v[152:155], v143 offset:1024
	ds_read_b128 v[156:159], v143 offset:2048
	ds_read_b128 v[160:163], v143 offset:3072
	s_add_u32 s24, s22, 0xfff80080
	s_addc_u32 s25, s23, -1
	s_cmp_eq_u32 s53, 28
	s_cselect_b32 s27, s15, s25
	s_cselect_b32 s26, s49, s24
	s_cselect_b32 s25, s13, s52
	s_cselect_b32 s24, s50, s51

	s_add_i32 m0, s21, 0xc000
	ds_read_b128 v[164:167], v145
	ds_read_b128 v[176:179], v145 offset:1024
	ds_read_b128 v[180:183], v145 offset:2048
	ds_read_b128 v[184:187], v145 offset:3072
	ds_read_b128 v[188:191], v145 offset:4096
	ds_read_b128 v[192:195], v145 offset:5120
	ds_read_b128 v[196:199], v145 offset:6144
	ds_read_b128 v[200:203], v145 offset:7168
	global_load_lds_dwordx4 v128, s[22:23]
	s_add_i32 m0, s21, 0xe000
	s_nop 0

	global_load_lds_dwordx4 v130, s[22:23]
	s_waitcnt lgkmcnt(8)
	s_barrier
	s_waitcnt lgkmcnt(0)


	v_mfma_f32_16x16x32_bf16 v[124:127], v[148:151], v[164:167], v[124:127]
	v_mfma_f32_16x16x32_bf16 v[120:123], v[156:159], v[164:167], v[120:123]
	v_mfma_f32_16x16x32_bf16 v[116:119], v[148:151], v[180:183], v[116:119]
	v_mfma_f32_16x16x32_bf16 v[104:107], v[156:159], v[180:183], v[104:107]
	v_mfma_f32_16x16x32_bf16 v[96:99], v[148:151], v[188:191], v[96:99]
	v_mfma_f32_16x16x32_bf16 v[88:91], v[156:159], v[188:191], v[88:91]
	v_mfma_f32_16x16x32_bf16 v[80:83], v[148:151], v[196:199], v[80:83]
	v_mfma_f32_16x16x32_bf16 v[72:75], v[156:159], v[196:199], v[72:75]
	v_mfma_f32_16x16x32_bf16 v[124:127], v[152:155], v[176:179], v[124:127]
	v_mfma_f32_16x16x32_bf16 v[120:123], v[160:163], v[176:179], v[120:123]
	v_mfma_f32_16x16x32_bf16 v[116:119], v[152:155], v[184:187], v[116:119]
	v_mfma_f32_16x16x32_bf16 v[104:107], v[160:163], v[184:187], v[104:107]
	v_mfma_f32_16x16x32_bf16 v[96:99], v[152:155], v[192:195], v[96:99]
	v_mfma_f32_16x16x32_bf16 v[88:91], v[160:163], v[192:195], v[88:91]
	v_mfma_f32_16x16x32_bf16 v[80:83], v[152:155], v[200:203], v[80:83]
	v_mfma_f32_16x16x32_bf16 v[72:75], v[160:163], v[200:203], v[72:75]

	s_barrier
	s_add_i32 s54, s45, s31
	v_lshl_add_u64 v[136:137], s[24:25], 0, v[172:173]
	s_mov_b32 m0, s54
	ds_read_b128 v[204:207], v147
	ds_read_b128 v[218:221], v147 offset:1024
	ds_read_b128 v[222:225], v147 offset:2048
	ds_read_b128 v[226:229], v147 offset:3072
	global_load_lds_dwordx4 v[136:137], off
	s_add_i32 m0, s54, 0x2000
	v_lshl_add_u64 v[140:141], s[24:25], 0, v[174:175]

	global_load_lds_dwordx4 v[140:141], off
	s_barrier
	s_waitcnt lgkmcnt(0)


	v_mfma_f32_16x16x32_bf16 v[112:115], v[204:207], v[164:167], v[112:115]
	v_mfma_f32_16x16x32_bf16 v[108:111], v[222:225], v[164:167], v[108:111]
	v_mfma_f32_16x16x32_bf16 v[100:103], v[204:207], v[180:183], v[100:103]
	v_mfma_f32_16x16x32_bf16 v[92:95], v[222:225], v[180:183], v[92:95]
	v_mfma_f32_16x16x32_bf16 v[84:87], v[204:207], v[188:191], v[84:87]
	v_mfma_f32_16x16x32_bf16 v[76:79], v[222:225], v[188:191], v[76:79]
	v_mfma_f32_16x16x32_bf16 v[68:71], v[204:207], v[196:199], v[68:71]
	v_mfma_f32_16x16x32_bf16 v[64:67], v[222:225], v[196:199], v[64:67]
	v_mfma_f32_16x16x32_bf16 v[112:115], v[218:221], v[176:179], v[112:115]
	v_mfma_f32_16x16x32_bf16 v[108:111], v[226:229], v[176:179], v[108:111]
	v_mfma_f32_16x16x32_bf16 v[100:103], v[218:221], v[184:187], v[100:103]
	v_mfma_f32_16x16x32_bf16 v[92:95], v[226:229], v[184:187], v[92:95]
	v_mfma_f32_16x16x32_bf16 v[84:87], v[218:221], v[192:195], v[84:87]
	v_mfma_f32_16x16x32_bf16 v[76:79], v[226:229], v[192:195], v[76:79]
	v_mfma_f32_16x16x32_bf16 v[68:71], v[218:221], v[200:203], v[68:71]
	v_mfma_f32_16x16x32_bf16 v[64:67], v[226:229], v[200:203], v[64:67]

	s_mov_b32 m0, s21
	v_lshl_add_u64 v[208:209], s[26:27], 0, v[172:173]
	s_barrier
	ds_read_b128 v[164:167], v145 offset:16384
	ds_read_b128 v[176:179], v145 offset:17408
	ds_read_b128 v[180:183], v145 offset:18432
	ds_read_b128 v[184:187], v145 offset:19456
	ds_read_b128 v[188:191], v145 offset:20480
	ds_read_b128 v[192:195], v145 offset:21504
	ds_read_b128 v[196:199], v145 offset:22528
	ds_read_b128 v[200:203], v145 offset:23552
	global_load_lds_dwordx4 v[208:209], off
	s_mov_b32 m0, s35
	v_lshl_add_u64 v[230:231], s[26:27], 0, v[174:175]

	global_load_lds_dwordx4 v[230:231], off
	s_barrier
	s_waitcnt lgkmcnt(0)


	v_mfma_f32_16x16x32_bf16 v[60:63], v[148:151], v[164:167], v[60:63]
	v_mfma_f32_16x16x32_bf16 v[56:59], v[156:159], v[164:167], v[56:59]
	v_mfma_f32_16x16x32_bf16 v[48:51], v[148:151], v[180:183], v[48:51]
	v_mfma_f32_16x16x32_bf16 v[40:43], v[156:159], v[180:183], v[40:43]
	v_mfma_f32_16x16x32_bf16 v[32:35], v[148:151], v[188:191], v[32:35]
	v_mfma_f32_16x16x32_bf16 v[24:27], v[156:159], v[188:191], v[24:27]
	v_mfma_f32_16x16x32_bf16 v[16:19], v[148:151], v[196:199], v[16:19]
	v_mfma_f32_16x16x32_bf16 v[8:11], v[156:159], v[196:199], v[8:11]
	v_mfma_f32_16x16x32_bf16 v[60:63], v[152:155], v[176:179], v[60:63]
	v_mfma_f32_16x16x32_bf16 v[56:59], v[160:163], v[176:179], v[56:59]
	v_mfma_f32_16x16x32_bf16 v[48:51], v[152:155], v[184:187], v[48:51]
	v_mfma_f32_16x16x32_bf16 v[40:43], v[160:163], v[184:187], v[40:43]
	v_mfma_f32_16x16x32_bf16 v[32:35], v[152:155], v[192:195], v[32:35]
	v_mfma_f32_16x16x32_bf16 v[24:27], v[160:163], v[192:195], v[24:27]
	v_mfma_f32_16x16x32_bf16 v[16:19], v[152:155], v[200:203], v[16:19]
	v_mfma_f32_16x16x32_bf16 v[8:11], v[160:163], v[200:203], v[8:11]

	s_barrier
	s_add_u32 s54, s24, 0x80000
	s_addc_u32 s55, s25, 0
	s_add_i32 s56, s46, s31
	s_mov_b32 m0, s56
	s_nop 0

	global_load_lds_dwordx4 v172, s[54:55]
	s_add_i32 m0, s56, 0x2000
	s_nop 0

	global_load_lds_dwordx4 v174, s[54:55]
	s_waitcnt vmcnt(6)
	s_barrier

	v_mfma_f32_16x16x32_bf16 v[52:55], v[204:207], v[164:167], v[52:55]
	v_mfma_f32_16x16x32_bf16 v[44:47], v[222:225], v[164:167], v[44:47]
	v_mfma_f32_16x16x32_bf16 v[36:39], v[204:207], v[180:183], v[36:39]
	v_mfma_f32_16x16x32_bf16 v[28:31], v[222:225], v[180:183], v[28:31]
	v_mfma_f32_16x16x32_bf16 v[20:23], v[204:207], v[188:191], v[20:23]
	v_mfma_f32_16x16x32_bf16 v[12:15], v[222:225], v[188:191], v[12:15]
	v_mfma_f32_16x16x32_bf16 v[4:7], v[204:207], v[196:199], v[4:7]
	v_mfma_f32_16x16x32_bf16 v[0:3], v[222:225], v[196:199], v[0:3]
	v_mfma_f32_16x16x32_bf16 v[52:55], v[218:221], v[176:179], v[52:55]
	v_mfma_f32_16x16x32_bf16 v[44:47], v[226:229], v[176:179], v[44:47]
	v_mfma_f32_16x16x32_bf16 v[36:39], v[218:221], v[184:187], v[36:39]
	v_mfma_f32_16x16x32_bf16 v[28:31], v[226:229], v[184:187], v[28:31]
	v_mfma_f32_16x16x32_bf16 v[20:23], v[218:221], v[192:195], v[20:23]
	v_mfma_f32_16x16x32_bf16 v[12:15], v[226:229], v[192:195], v[12:15]
	v_mfma_f32_16x16x32_bf16 v[4:7], v[218:221], v[200:203], v[4:7]
	v_mfma_f32_16x16x32_bf16 v[0:3], v[226:229], v[200:203], v[0:3]

	s_add_i32 s54, 0, 0x18000
	v_add_u32_e32 v138, s54, v139
	s_barrier
	ds_read_b128 v[148:151], v138
	ds_read_b128 v[152:155], v138 offset:1024
	ds_read_b128 v[156:159], v138 offset:2048
	ds_read_b128 v[160:163], v138 offset:3072
	s_add_u32 s26, s26, 0x80000
	s_addc_u32 s27, s27, 0
	s_mov_b32 m0, s36

	ds_read_b128 v[164:167], v145 offset:32768
	ds_read_b128 v[176:179], v145 offset:33792
	ds_read_b128 v[180:183], v145 offset:34816
	ds_read_b128 v[184:187], v145 offset:35840
	ds_read_b128 v[188:191], v145 offset:36864
	ds_read_b128 v[192:195], v145 offset:37888
	ds_read_b128 v[196:199], v145 offset:38912
	ds_read_b128 v[200:203], v145 offset:39936
	global_load_lds_dwordx4 v172, s[26:27]
	s_mov_b32 m0, s37
	s_nop 0

	global_load_lds_dwordx4 v174, s[26:27]
	s_waitcnt lgkmcnt(8)
	s_barrier
	s_waitcnt lgkmcnt(0)


	v_mfma_f32_16x16x32_bf16 v[124:127], v[148:151], v[164:167], v[124:127]
	v_mfma_f32_16x16x32_bf16 v[120:123], v[156:159], v[164:167], v[120:123]
	v_mfma_f32_16x16x32_bf16 v[116:119], v[148:151], v[180:183], v[116:119]
	v_mfma_f32_16x16x32_bf16 v[104:107], v[156:159], v[180:183], v[104:107]
	v_mfma_f32_16x16x32_bf16 v[96:99], v[148:151], v[188:191], v[96:99]
	v_mfma_f32_16x16x32_bf16 v[88:91], v[156:159], v[188:191], v[88:91]
	v_mfma_f32_16x16x32_bf16 v[80:83], v[148:151], v[196:199], v[80:83]
	v_mfma_f32_16x16x32_bf16 v[72:75], v[156:159], v[196:199], v[72:75]
	v_mfma_f32_16x16x32_bf16 v[124:127], v[152:155], v[176:179], v[124:127]
	v_mfma_f32_16x16x32_bf16 v[120:123], v[160:163], v[176:179], v[120:123]
	v_mfma_f32_16x16x32_bf16 v[116:119], v[152:155], v[184:187], v[116:119]
	v_mfma_f32_16x16x32_bf16 v[104:107], v[160:163], v[184:187], v[104:107]
	v_mfma_f32_16x16x32_bf16 v[96:99], v[152:155], v[192:195], v[96:99]
	v_mfma_f32_16x16x32_bf16 v[88:91], v[160:163], v[192:195], v[88:91]
	v_mfma_f32_16x16x32_bf16 v[80:83], v[152:155], v[200:203], v[80:83]
	v_mfma_f32_16x16x32_bf16 v[72:75], v[160:163], v[200:203], v[72:75]

	s_barrier
	s_add_i32 s26, 0, 0x1c000
	s_add_i32 s27, s54, s31
	v_add_u32_e32 v138, s26, v139
	v_lshl_add_u64 v[136:137], v[136:137], 0, s[10:11]
	s_mov_b32 m0, s27
	ds_read_b128 v[204:207], v138
	ds_read_b128 v[218:221], v138 offset:1024
	ds_read_b128 v[222:225], v138 offset:2048
	ds_read_b128 v[226:229], v138 offset:3072
	global_load_lds_dwordx4 v[136:137], off
	s_add_i32 m0, s27, 0x2000
	v_lshl_add_u64 v[136:137], v[140:141], 0, s[10:11]

	global_load_lds_dwordx4 v[136:137], off
	s_barrier
	s_waitcnt lgkmcnt(0)


	v_mfma_f32_16x16x32_bf16 v[112:115], v[204:207], v[164:167], v[112:115]
	v_mfma_f32_16x16x32_bf16 v[108:111], v[222:225], v[164:167], v[108:111]
	v_mfma_f32_16x16x32_bf16 v[100:103], v[204:207], v[180:183], v[100:103]
	v_mfma_f32_16x16x32_bf16 v[92:95], v[222:225], v[180:183], v[92:95]
	v_mfma_f32_16x16x32_bf16 v[84:87], v[204:207], v[188:191], v[84:87]
	v_mfma_f32_16x16x32_bf16 v[76:79], v[222:225], v[188:191], v[76:79]
	v_mfma_f32_16x16x32_bf16 v[68:71], v[204:207], v[196:199], v[68:71]
	v_mfma_f32_16x16x32_bf16 v[64:67], v[222:225], v[196:199], v[64:67]
	v_mfma_f32_16x16x32_bf16 v[112:115], v[218:221], v[176:179], v[112:115]
	v_mfma_f32_16x16x32_bf16 v[108:111], v[226:229], v[176:179], v[108:111]
	v_mfma_f32_16x16x32_bf16 v[100:103], v[218:221], v[184:187], v[100:103]
	v_mfma_f32_16x16x32_bf16 v[92:95], v[226:229], v[184:187], v[92:95]
	v_mfma_f32_16x16x32_bf16 v[84:87], v[218:221], v[192:195], v[84:87]
	v_mfma_f32_16x16x32_bf16 v[76:79], v[226:229], v[192:195], v[76:79]
	v_mfma_f32_16x16x32_bf16 v[68:71], v[218:221], v[200:203], v[68:71]
	v_mfma_f32_16x16x32_bf16 v[64:67], v[226:229], v[200:203], v[64:67]

	s_mov_b32 m0, s41
	v_lshl_add_u64 v[136:137], v[208:209], 0, s[10:11]
	s_barrier
	ds_read_b128 v[164:167], v145 offset:49152
	ds_read_b128 v[176:179], v145 offset:50176
	ds_read_b128 v[180:183], v145 offset:51200
	ds_read_b128 v[184:187], v145 offset:52224
	ds_read_b128 v[188:191], v145 offset:53248
	ds_read_b128 v[192:195], v145 offset:54272
	ds_read_b128 v[196:199], v145 offset:55296
	ds_read_b128 v[200:203], v145 offset:56320
	global_load_lds_dwordx4 v[136:137], off
	s_mov_b32 m0, s42
	v_lshl_add_u64 v[136:137], v[230:231], 0, s[10:11]

	global_load_lds_dwordx4 v[136:137], off
	s_barrier
	s_waitcnt lgkmcnt(0)


	v_mfma_f32_16x16x32_bf16 v[60:63], v[148:151], v[164:167], v[60:63]
	v_mfma_f32_16x16x32_bf16 v[56:59], v[156:159], v[164:167], v[56:59]
	v_mfma_f32_16x16x32_bf16 v[48:51], v[148:151], v[180:183], v[48:51]
	v_mfma_f32_16x16x32_bf16 v[40:43], v[156:159], v[180:183], v[40:43]
	v_mfma_f32_16x16x32_bf16 v[32:35], v[148:151], v[188:191], v[32:35]
	v_mfma_f32_16x16x32_bf16 v[24:27], v[156:159], v[188:191], v[24:27]
	v_mfma_f32_16x16x32_bf16 v[16:19], v[148:151], v[196:199], v[16:19]
	v_mfma_f32_16x16x32_bf16 v[8:11], v[156:159], v[196:199], v[8:11]
	v_mfma_f32_16x16x32_bf16 v[60:63], v[152:155], v[176:179], v[60:63]
	v_mfma_f32_16x16x32_bf16 v[56:59], v[160:163], v[176:179], v[56:59]
	v_mfma_f32_16x16x32_bf16 v[48:51], v[152:155], v[184:187], v[48:51]
	v_mfma_f32_16x16x32_bf16 v[40:43], v[160:163], v[184:187], v[40:43]
	v_mfma_f32_16x16x32_bf16 v[32:35], v[152:155], v[192:195], v[32:35]
	v_mfma_f32_16x16x32_bf16 v[24:27], v[160:163], v[192:195], v[24:27]
	v_mfma_f32_16x16x32_bf16 v[16:19], v[152:155], v[200:203], v[16:19]
	v_mfma_f32_16x16x32_bf16 v[8:11], v[160:163], v[200:203], v[8:11]

	s_barrier
	s_add_u32 s24, s24, 0x80080
	s_addc_u32 s25, s25, 0
	s_add_i32 s26, s26, s31
	s_mov_b32 m0, s26
	s_nop 0

	global_load_lds_dwordx4 v172, s[24:25]
	s_add_i32 m0, s26, 0x2000
	s_nop 0

	global_load_lds_dwordx4 v174, s[24:25]
	s_waitcnt vmcnt(6)
	s_barrier

	v_mfma_f32_16x16x32_bf16 v[52:55], v[204:207], v[164:167], v[52:55]
	v_mfma_f32_16x16x32_bf16 v[44:47], v[222:225], v[164:167], v[44:47]
	v_mfma_f32_16x16x32_bf16 v[36:39], v[204:207], v[180:183], v[36:39]
	v_mfma_f32_16x16x32_bf16 v[28:31], v[222:225], v[180:183], v[28:31]
	v_mfma_f32_16x16x32_bf16 v[20:23], v[204:207], v[188:191], v[20:23]
	v_mfma_f32_16x16x32_bf16 v[12:15], v[222:225], v[188:191], v[12:15]
	v_mfma_f32_16x16x32_bf16 v[4:7], v[204:207], v[196:199], v[4:7]
	v_mfma_f32_16x16x32_bf16 v[0:3], v[222:225], v[196:199], v[0:3]
	v_mfma_f32_16x16x32_bf16 v[52:55], v[218:221], v[176:179], v[52:55]
	v_mfma_f32_16x16x32_bf16 v[44:47], v[226:229], v[176:179], v[44:47]
	v_mfma_f32_16x16x32_bf16 v[36:39], v[218:221], v[184:187], v[36:39]
	v_mfma_f32_16x16x32_bf16 v[28:31], v[226:229], v[184:187], v[28:31]
	v_mfma_f32_16x16x32_bf16 v[20:23], v[218:221], v[192:195], v[20:23]
	v_mfma_f32_16x16x32_bf16 v[12:15], v[226:229], v[192:195], v[12:15]
	v_mfma_f32_16x16x32_bf16 v[4:7], v[218:221], v[200:203], v[4:7]
	v_mfma_f32_16x16x32_bf16 v[0:3], v[226:229], v[200:203], v[0:3]

	s_add_i32 s53, s53, 2
	s_add_u32 s22, s22, 0x100
	s_addc_u32 s23, s23, 0
	s_add_u32 s51, s51, 0x100
	s_addc_u32 s52, s52, 0
	s_cmp_gt_u32 s53, 29
	s_barrier
	s_cbranch_scc0 .LBB0_1167
	s_lshl_b32 s13, s20, 8
	v_mov_b32_e32 v138, v210
	v_mov_b32_e32 v142, v169
	s_add_i32 s13, s13, s39
	s_lshl_b32 s15, s48, 7
	v_add_u32_e32 v136, s13, v142
	v_ashrrev_i32_e32 v137, 31, v136
	v_lshl_add_u64 v[140:141], v[136:137], 2, s[2:3]
	global_load_dword v154, v[140:141], off
	global_load_dword v152, v[140:141], off offset:64
	v_lshl_add_u32 v138, v138, 4, v142
	v_and_b32_e32 v142, 3, v142
	v_ashrrev_i32_e32 v144, 2, v138
	v_and_b32_e32 v138, -4, v138
	v_lshl_or_b32 v146, v142, 2, s15
	v_add_u32_e32 v151, s13, v144
	v_lshl_add_u32 v149, v142, 6, v138
	v_or_b32_e32 v156, s40, v146
	global_load_dword v150, v[140:141], off offset:128
	global_load_dword v148, v[140:141], off offset:192
	global_load_dword v146, v[140:141], off offset:512
	global_load_dword v144, v[140:141], off offset:576
	global_load_dword v142, v[140:141], off offset:640
	global_load_dword v138, v[140:141], off offset:704
	v_mov_b64_e32 v[136:137], s[0:1]
	v_ashrrev_i32_e32 v157, 31, v156
	v_mad_i64_i32 v[158:159], s[22:23], v151, s47, v[136:137]
	v_lshlrev_b64 v[140:141], 1, v[156:157]
	v_lshl_add_u64 v[156:157], v[158:159], 0, v[140:141]
	v_add_u32_e32 v153, 16, v151
	s_and_b64 vcc, exec, s[4:5]
	s_mov_b32 s48, s12
	s_mov_b32 s20, s14
	s_mov_b64 s[24:25], s[18:19]
	s_waitcnt vmcnt(0)
	v_pk_mul_f32 v[126:127], v[126:127], v[154:155] op_sel_hi:[1,0]
	v_pk_mul_f32 v[124:125], v[124:125], v[154:155] op_sel_hi:[1,0]
	v_pk_mul_f32 v[114:115], v[114:115], v[154:155] op_sel_hi:[1,0]
	v_pk_mul_f32 v[112:113], v[112:113], v[154:155] op_sel_hi:[1,0]
	v_pk_mul_f32 v[122:123], v[122:123], v[154:155] op_sel_hi:[1,0]
	v_pk_mul_f32 v[120:121], v[120:121], v[154:155] op_sel_hi:[1,0]
	v_pk_mul_f32 v[110:111], v[110:111], v[154:155] op_sel_hi:[1,0]
	v_pk_mul_f32 v[108:109], v[108:109], v[154:155] op_sel_hi:[1,0]
	v_mul_f32_e32 v154, 0xbfb8aa3b, v124
	v_mul_f32_e32 v155, 0xbfb8aa3b, v125
	v_mul_f32_e32 v158, 0xbfb8aa3b, v126
	v_mul_f32_e32 v159, 0xbfb8aa3b, v127
	v_mul_f32_e32 v160, 0xbfb8aa3b, v120
	v_mul_f32_e32 v161, 0xbfb8aa3b, v121
	v_mul_f32_e32 v162, 0xbfb8aa3b, v122
	v_mul_f32_e32 v163, 0xbfb8aa3b, v123
	v_exp_f32_e32 v154, v154
	v_exp_f32_e32 v155, v155
	v_exp_f32_e32 v158, v158
	v_exp_f32_e32 v159, v159
	v_exp_f32_e32 v160, v160
	v_exp_f32_e32 v161, v161
	v_exp_f32_e32 v162, v162
	v_exp_f32_e32 v163, v163
	v_add_f32_e32 v154, 1.0, v154
	v_add_f32_e32 v155, 1.0, v155
	v_add_f32_e32 v158, 1.0, v158
	v_add_f32_e32 v159, 1.0, v159
	v_add_f32_e32 v160, 1.0, v160
	v_add_f32_e32 v161, 1.0, v161
	v_add_f32_e32 v162, 1.0, v162
	v_add_f32_e32 v163, 1.0, v163
	v_rcp_f32_e32 v154, v154
	v_rcp_f32_e32 v155, v155
	v_rcp_f32_e32 v158, v158
	v_rcp_f32_e32 v159, v159
	v_rcp_f32_e32 v160, v160
	v_rcp_f32_e32 v161, v161
	v_rcp_f32_e32 v162, v162
	v_rcp_f32_e32 v163, v163
	v_pk_mul_f32 v[124:125], v[124:125], v[154:155]
	v_pk_mul_f32 v[126:127], v[126:127], v[158:159]
	v_pk_mul_f32 v[120:121], v[120:121], v[160:161]
	v_pk_mul_f32 v[122:123], v[122:123], v[162:163]
	v_pk_mul_f32 v[112:113], v[112:113], v[124:125]
	v_pk_mul_f32 v[114:115], v[114:115], v[126:127]
	v_pk_mul_f32 v[118:119], v[118:119], v[152:153] op_sel_hi:[1,0]
	v_pk_mul_f32 v[116:117], v[116:117], v[152:153] op_sel_hi:[1,0]
	v_pk_mul_f32 v[108:109], v[108:109], v[120:121]
	v_pk_mul_f32 v[110:111], v[110:111], v[122:123]
	v_cvt_pk_bf16_f32 v112, v112, v113
	v_cvt_pk_bf16_f32 v113, v114, v115
	v_mul_f32_e32 v164, 0xbfb8aa3b, v116
	v_mul_f32_e32 v165, 0xbfb8aa3b, v117
	v_mul_f32_e32 v166, 0xbfb8aa3b, v118
	v_mul_f32_e32 v167, 0xbfb8aa3b, v119
	v_cvt_pk_bf16_f32 v114, v108, v109
	v_cvt_pk_bf16_f32 v111, v110, v111
	ds_bpermute_b32 v108, v149, v112
	ds_bpermute_b32 v109, v149, v113
	v_exp_f32_e32 v164, v164
	v_exp_f32_e32 v165, v165
	v_exp_f32_e32 v166, v166
	v_exp_f32_e32 v167, v167
	ds_bpermute_b32 v110, v149, v114
	ds_bpermute_b32 v111, v149, v111
	v_add_f32_e32 v164, 1.0, v164
	v_add_f32_e32 v113, 1.0, v165
	s_waitcnt lgkmcnt(0)
	global_store_dwordx2 v[156:157], v[108:109], off
	global_store_dwordx2 v[156:157], v[110:111], off offset:32
	v_add_f32_e32 v108, 1.0, v166
	v_add_f32_e32 v109, 1.0, v167
	v_rcp_f32_e32 v112, v164
	v_rcp_f32_e32 v113, v113
	v_rcp_f32_e32 v108, v108
	v_rcp_f32_e32 v109, v109
	v_pk_mul_f32 v[102:103], v[102:103], v[152:153] op_sel_hi:[1,0]
	v_pk_mul_f32 v[100:101], v[100:101], v[152:153] op_sel_hi:[1,0]
	v_pk_mul_f32 v[110:111], v[116:117], v[112:113]
	v_pk_mul_f32 v[108:109], v[118:119], v[108:109]
	v_pk_mul_f32 v[100:101], v[100:101], v[110:111]
	v_pk_mul_f32 v[102:103], v[102:103], v[108:109]
	v_cvt_pk_bf16_f32 v100, v100, v101
	v_cvt_pk_bf16_f32 v101, v102, v103
	v_pk_mul_f32 v[102:103], v[106:107], v[152:153] op_sel_hi:[1,0]
	v_pk_mul_f32 v[104:105], v[104:105], v[152:153] op_sel_hi:[1,0]
	v_mul_f32_e32 v108, 0xbfb8aa3b, v102
	v_mul_f32_e32 v106, 0xbfb8aa3b, v104
	v_mul_f32_e32 v107, 0xbfb8aa3b, v105
	v_mul_f32_e32 v109, 0xbfb8aa3b, v103
	v_exp_f32_e32 v106, v106
	v_exp_f32_e32 v107, v107
	v_exp_f32_e32 v108, v108
	v_exp_f32_e32 v109, v109
	v_add_f32_e32 v106, 1.0, v106
	v_add_f32_e32 v107, 1.0, v107
	v_add_f32_e32 v108, 1.0, v108
	v_add_f32_e32 v109, 1.0, v109
	v_rcp_f32_e32 v106, v106
	v_rcp_f32_e32 v107, v107
	v_rcp_f32_e32 v108, v108
	v_rcp_f32_e32 v109, v109
	v_pk_mul_f32 v[94:95], v[94:95], v[152:153] op_sel_hi:[1,0]
	v_pk_mul_f32 v[92:93], v[92:93], v[152:153] op_sel_hi:[1,0]
	v_pk_mul_f32 v[104:105], v[104:105], v[106:107]
	v_pk_mul_f32 v[102:103], v[102:103], v[108:109]
	v_pk_mul_f32 v[92:93], v[92:93], v[104:105]
	v_pk_mul_f32 v[94:95], v[94:95], v[102:103]
	ds_bpermute_b32 v100, v149, v100
	ds_bpermute_b32 v101, v149, v101
	v_cvt_pk_bf16_f32 v92, v92, v93
	v_cvt_pk_bf16_f32 v93, v94, v95
	ds_bpermute_b32 v92, v149, v92
	ds_bpermute_b32 v93, v149, v93
	v_mad_i64_i32 v[94:95], s[22:23], v153, s47, v[136:137]
	v_lshl_add_u64 v[94:95], v[94:95], 0, v[140:141]
	s_waitcnt lgkmcnt(2)
	global_store_dwordx2 v[94:95], v[100:101], off
	s_waitcnt lgkmcnt(0)
	global_store_dwordx2 v[94:95], v[92:93], off offset:32
	v_pk_mul_f32 v[92:93], v[98:99], v[150:151] op_sel_hi:[1,0]
	v_pk_mul_f32 v[94:95], v[96:97], v[150:151] op_sel_hi:[1,0]
	v_mul_f32_e32 v98, 0xbfb8aa3b, v92
	v_mul_f32_e32 v96, 0xbfb8aa3b, v94
	v_mul_f32_e32 v97, 0xbfb8aa3b, v95
	v_mul_f32_e32 v99, 0xbfb8aa3b, v93
	v_exp_f32_e32 v96, v96
	v_exp_f32_e32 v97, v97
	v_exp_f32_e32 v98, v98
	v_exp_f32_e32 v99, v99
	v_add_f32_e32 v96, 1.0, v96
	v_add_f32_e32 v97, 1.0, v97
	v_add_f32_e32 v98, 1.0, v98
	v_add_f32_e32 v99, 1.0, v99
	v_rcp_f32_e32 v96, v96
	v_rcp_f32_e32 v97, v97
	v_rcp_f32_e32 v98, v98
	v_rcp_f32_e32 v99, v99
	v_pk_mul_f32 v[86:87], v[86:87], v[150:151] op_sel_hi:[1,0]
	v_pk_mul_f32 v[84:85], v[84:85], v[150:151] op_sel_hi:[1,0]
	v_pk_mul_f32 v[94:95], v[94:95], v[96:97]
	v_pk_mul_f32 v[92:93], v[92:93], v[98:99]
	v_pk_mul_f32 v[84:85], v[84:85], v[94:95]
	v_pk_mul_f32 v[86:87], v[86:87], v[92:93]
	v_cvt_pk_bf16_f32 v84, v84, v85
	v_cvt_pk_bf16_f32 v85, v86, v87
	v_pk_mul_f32 v[86:87], v[90:91], v[150:151] op_sel_hi:[1,0]
	v_pk_mul_f32 v[88:89], v[88:89], v[150:151] op_sel_hi:[1,0]
	v_mul_f32_e32 v92, 0xbfb8aa3b, v86
	v_mul_f32_e32 v90, 0xbfb8aa3b, v88
	v_mul_f32_e32 v91, 0xbfb8aa3b, v89
	v_mul_f32_e32 v93, 0xbfb8aa3b, v87
	v_exp_f32_e32 v90, v90
	v_exp_f32_e32 v91, v91
	v_exp_f32_e32 v92, v92
	v_exp_f32_e32 v93, v93
	v_add_f32_e32 v90, 1.0, v90
	v_add_f32_e32 v91, 1.0, v91
	v_add_f32_e32 v92, 1.0, v92
	v_add_f32_e32 v93, 1.0, v93
	v_rcp_f32_e32 v90, v90
	v_rcp_f32_e32 v91, v91
	v_rcp_f32_e32 v92, v92
	v_rcp_f32_e32 v93, v93
	v_pk_mul_f32 v[78:79], v[78:79], v[150:151] op_sel_hi:[1,0]
	v_pk_mul_f32 v[76:77], v[76:77], v[150:151] op_sel_hi:[1,0]
	v_pk_mul_f32 v[88:89], v[88:89], v[90:91]
	v_pk_mul_f32 v[86:87], v[86:87], v[92:93]
	v_pk_mul_f32 v[76:77], v[76:77], v[88:89]
	v_pk_mul_f32 v[78:79], v[78:79], v[86:87]
	ds_bpermute_b32 v84, v149, v84
	ds_bpermute_b32 v85, v149, v85
	v_cvt_pk_bf16_f32 v76, v76, v77
	v_cvt_pk_bf16_f32 v77, v78, v79
	ds_bpermute_b32 v76, v149, v76
	ds_bpermute_b32 v77, v149, v77
	v_add_u32_e32 v100, 32, v151
	v_mad_i64_i32 v[78:79], s[22:23], v100, s47, v[136:137]
	v_lshl_add_u64 v[78:79], v[78:79], 0, v[140:141]
	s_waitcnt lgkmcnt(2)
	global_store_dwordx2 v[78:79], v[84:85], off
	s_waitcnt lgkmcnt(0)
	global_store_dwordx2 v[78:79], v[76:77], off offset:32
	v_pk_mul_f32 v[76:77], v[82:83], v[148:149] op_sel_hi:[1,0]
	v_pk_mul_f32 v[78:79], v[80:81], v[148:149] op_sel_hi:[1,0]
	v_mul_f32_e32 v82, 0xbfb8aa3b, v76
	v_mul_f32_e32 v80, 0xbfb8aa3b, v78
	v_mul_f32_e32 v81, 0xbfb8aa3b, v79
	v_mul_f32_e32 v83, 0xbfb8aa3b, v77
	v_exp_f32_e32 v80, v80
	v_exp_f32_e32 v81, v81
	v_exp_f32_e32 v82, v82
	v_exp_f32_e32 v83, v83
	v_add_f32_e32 v80, 1.0, v80
	v_add_f32_e32 v81, 1.0, v81
	v_add_f32_e32 v82, 1.0, v82
	v_add_f32_e32 v83, 1.0, v83
	v_rcp_f32_e32 v80, v80
	v_rcp_f32_e32 v81, v81
	v_rcp_f32_e32 v82, v82
	v_rcp_f32_e32 v83, v83
	v_pk_mul_f32 v[70:71], v[70:71], v[148:149] op_sel_hi:[1,0]
	v_pk_mul_f32 v[68:69], v[68:69], v[148:149] op_sel_hi:[1,0]
	v_pk_mul_f32 v[78:79], v[78:79], v[80:81]
	v_pk_mul_f32 v[76:77], v[76:77], v[82:83]
	v_pk_mul_f32 v[68:69], v[68:69], v[78:79]
	v_pk_mul_f32 v[70:71], v[70:71], v[76:77]
	v_cvt_pk_bf16_f32 v68, v68, v69
	v_cvt_pk_bf16_f32 v69, v70, v71
	v_pk_mul_f32 v[70:71], v[74:75], v[148:149] op_sel_hi:[1,0]
	v_pk_mul_f32 v[72:73], v[72:73], v[148:149] op_sel_hi:[1,0]
	v_mul_f32_e32 v76, 0xbfb8aa3b, v70
	v_mul_f32_e32 v74, 0xbfb8aa3b, v72
	v_mul_f32_e32 v75, 0xbfb8aa3b, v73
	v_mul_f32_e32 v77, 0xbfb8aa3b, v71
	v_exp_f32_e32 v74, v74
	v_exp_f32_e32 v75, v75
	v_exp_f32_e32 v76, v76
	v_exp_f32_e32 v77, v77
	v_add_f32_e32 v74, 1.0, v74
	v_add_f32_e32 v75, 1.0, v75
	v_add_f32_e32 v76, 1.0, v76
	v_add_f32_e32 v77, 1.0, v77
	v_rcp_f32_e32 v74, v74
	v_rcp_f32_e32 v75, v75
	v_rcp_f32_e32 v76, v76
	v_rcp_f32_e32 v77, v77
	v_pk_mul_f32 v[66:67], v[66:67], v[148:149] op_sel_hi:[1,0]
	v_pk_mul_f32 v[64:65], v[64:65], v[148:149] op_sel_hi:[1,0]
	v_pk_mul_f32 v[72:73], v[72:73], v[74:75]
	v_pk_mul_f32 v[70:71], v[70:71], v[76:77]
	v_pk_mul_f32 v[64:65], v[64:65], v[72:73]
	v_pk_mul_f32 v[66:67], v[66:67], v[70:71]
	ds_bpermute_b32 v68, v149, v68
	ds_bpermute_b32 v69, v149, v69
	v_cvt_pk_bf16_f32 v64, v64, v65
	v_cvt_pk_bf16_f32 v65, v66, v67
	ds_bpermute_b32 v64, v149, v64
	ds_bpermute_b32 v65, v149, v65
	v_add_u32_e32 v84, 48, v151
	v_mad_i64_i32 v[66:67], s[22:23], v84, s47, v[136:137]
	v_lshl_add_u64 v[66:67], v[66:67], 0, v[140:141]
	v_pk_mul_f32 v[60:61], v[60:61], v[146:147] op_sel_hi:[1,0]
	s_waitcnt lgkmcnt(2)
	global_store_dwordx2 v[66:67], v[68:69], off
	s_waitcnt lgkmcnt(0)
	global_store_dwordx2 v[66:67], v[64:65], off offset:32
	v_pk_mul_f32 v[62:63], v[62:63], v[146:147] op_sel_hi:[1,0]
	v_mul_f32_e32 v64, 0xbfb8aa3b, v60
	v_mul_f32_e32 v65, 0xbfb8aa3b, v61
	v_exp_f32_e32 v64, v64
	v_exp_f32_e32 v65, v65
	v_mul_f32_e32 v66, 0xbfb8aa3b, v62
	v_mul_f32_e32 v67, 0xbfb8aa3b, v63
	v_exp_f32_e32 v66, v66
	v_exp_f32_e32 v67, v67
	v_add_f32_e32 v64, 1.0, v64
	v_add_f32_e32 v65, 1.0, v65
	v_rcp_f32_e32 v64, v64
	v_rcp_f32_e32 v65, v65
	v_add_f32_e32 v66, 1.0, v66
	v_add_f32_e32 v67, 1.0, v67
	v_rcp_f32_e32 v66, v66
	v_rcp_f32_e32 v67, v67
	v_pk_mul_f32 v[52:53], v[52:53], v[146:147] op_sel_hi:[1,0]
	v_pk_mul_f32 v[60:61], v[60:61], v[64:65]
	v_pk_mul_f32 v[54:55], v[54:55], v[146:147] op_sel_hi:[1,0]
	v_pk_mul_f32 v[52:53], v[52:53], v[60:61]
	v_pk_mul_f32 v[60:61], v[62:63], v[66:67]
	v_cvt_pk_bf16_f32 v52, v52, v53
	v_pk_mul_f32 v[54:55], v[54:55], v[60:61]
	v_pk_mul_f32 v[56:57], v[56:57], v[146:147] op_sel_hi:[1,0]
	v_cvt_pk_bf16_f32 v53, v54, v55
	v_pk_mul_f32 v[54:55], v[58:59], v[146:147] op_sel_hi:[1,0]
	v_mul_f32_e32 v58, 0xbfb8aa3b, v56
	v_mul_f32_e32 v59, 0xbfb8aa3b, v57
	v_mul_f32_e32 v60, 0xbfb8aa3b, v54
	v_mul_f32_e32 v61, 0xbfb8aa3b, v55
	v_exp_f32_e32 v58, v58
	v_exp_f32_e32 v59, v59
	v_exp_f32_e32 v60, v60
	v_exp_f32_e32 v61, v61
	v_add_f32_e32 v58, 1.0, v58
	v_add_f32_e32 v59, 1.0, v59
	v_add_f32_e32 v60, 1.0, v60
	v_add_f32_e32 v61, 1.0, v61
	v_rcp_f32_e32 v58, v58
	v_rcp_f32_e32 v59, v59
	v_rcp_f32_e32 v60, v60
	v_rcp_f32_e32 v61, v61
	v_pk_mul_f32 v[46:47], v[46:47], v[146:147] op_sel_hi:[1,0]
	v_pk_mul_f32 v[44:45], v[44:45], v[146:147] op_sel_hi:[1,0]
	v_pk_mul_f32 v[56:57], v[56:57], v[58:59]
	v_pk_mul_f32 v[54:55], v[54:55], v[60:61]
	v_pk_mul_f32 v[44:45], v[44:45], v[56:57]
	v_pk_mul_f32 v[46:47], v[46:47], v[54:55]
	ds_bpermute_b32 v52, v149, v52
	ds_bpermute_b32 v53, v149, v53
	v_cvt_pk_bf16_f32 v44, v44, v45
	v_cvt_pk_bf16_f32 v45, v46, v47
	ds_bpermute_b32 v44, v149, v44
	ds_bpermute_b32 v45, v149, v45
	v_add_u32_e32 v68, 0x80, v151
	v_mad_i64_i32 v[46:47], s[22:23], v68, s47, v[136:137]
	v_lshl_add_u64 v[46:47], v[46:47], 0, v[140:141]
	s_waitcnt lgkmcnt(2)
	global_store_dwordx2 v[46:47], v[52:53], off
	s_waitcnt lgkmcnt(0)
	global_store_dwordx2 v[46:47], v[44:45], off offset:32
	v_pk_mul_f32 v[44:45], v[50:51], v[144:145] op_sel_hi:[1,0]
	v_pk_mul_f32 v[46:47], v[48:49], v[144:145] op_sel_hi:[1,0]
	v_mul_f32_e32 v50, 0xbfb8aa3b, v44
	v_mul_f32_e32 v48, 0xbfb8aa3b, v46
	v_mul_f32_e32 v49, 0xbfb8aa3b, v47
	v_mul_f32_e32 v51, 0xbfb8aa3b, v45
	v_exp_f32_e32 v48, v48
	v_exp_f32_e32 v49, v49
	v_exp_f32_e32 v50, v50
	v_exp_f32_e32 v51, v51
	v_add_f32_e32 v48, 1.0, v48
	v_add_f32_e32 v49, 1.0, v49
	v_add_f32_e32 v50, 1.0, v50
	v_add_f32_e32 v51, 1.0, v51
	v_rcp_f32_e32 v48, v48
	v_rcp_f32_e32 v49, v49
	v_rcp_f32_e32 v50, v50
	v_rcp_f32_e32 v51, v51
	v_pk_mul_f32 v[38:39], v[38:39], v[144:145] op_sel_hi:[1,0]
	v_pk_mul_f32 v[36:37], v[36:37], v[144:145] op_sel_hi:[1,0]
	v_pk_mul_f32 v[46:47], v[46:47], v[48:49]
	v_pk_mul_f32 v[44:45], v[44:45], v[50:51]
	v_pk_mul_f32 v[36:37], v[36:37], v[46:47]
	v_pk_mul_f32 v[38:39], v[38:39], v[44:45]
	v_cvt_pk_bf16_f32 v36, v36, v37
	v_cvt_pk_bf16_f32 v37, v38, v39
	v_pk_mul_f32 v[38:39], v[42:43], v[144:145] op_sel_hi:[1,0]
	v_pk_mul_f32 v[40:41], v[40:41], v[144:145] op_sel_hi:[1,0]
	v_mul_f32_e32 v44, 0xbfb8aa3b, v38
	v_mul_f32_e32 v42, 0xbfb8aa3b, v40
	v_mul_f32_e32 v43, 0xbfb8aa3b, v41
	v_mul_f32_e32 v45, 0xbfb8aa3b, v39
	v_exp_f32_e32 v42, v42
	v_exp_f32_e32 v43, v43
	v_exp_f32_e32 v44, v44
	v_exp_f32_e32 v45, v45
	v_add_f32_e32 v42, 1.0, v42
	v_add_f32_e32 v43, 1.0, v43
	v_add_f32_e32 v44, 1.0, v44
	v_add_f32_e32 v45, 1.0, v45
	v_rcp_f32_e32 v42, v42
	v_rcp_f32_e32 v43, v43
	v_rcp_f32_e32 v44, v44
	v_rcp_f32_e32 v45, v45
	v_pk_mul_f32 v[30:31], v[30:31], v[144:145] op_sel_hi:[1,0]
	v_pk_mul_f32 v[28:29], v[28:29], v[144:145] op_sel_hi:[1,0]
	v_pk_mul_f32 v[40:41], v[40:41], v[42:43]
	v_pk_mul_f32 v[38:39], v[38:39], v[44:45]
	v_pk_mul_f32 v[28:29], v[28:29], v[40:41]
	v_pk_mul_f32 v[30:31], v[30:31], v[38:39]
	ds_bpermute_b32 v36, v149, v36
	ds_bpermute_b32 v37, v149, v37
	v_cvt_pk_bf16_f32 v28, v28, v29
	v_cvt_pk_bf16_f32 v29, v30, v31
	ds_bpermute_b32 v28, v149, v28
	ds_bpermute_b32 v29, v149, v29
	v_add_u32_e32 v52, 0x90, v151
	v_mad_i64_i32 v[30:31], s[22:23], v52, s47, v[136:137]
	v_lshl_add_u64 v[30:31], v[30:31], 0, v[140:141]
	s_waitcnt lgkmcnt(2)
	global_store_dwordx2 v[30:31], v[36:37], off
	s_waitcnt lgkmcnt(0)
	global_store_dwordx2 v[30:31], v[28:29], off offset:32
	v_pk_mul_f32 v[28:29], v[34:35], v[142:143] op_sel_hi:[1,0]
	v_pk_mul_f32 v[30:31], v[32:33], v[142:143] op_sel_hi:[1,0]
	v_mul_f32_e32 v34, 0xbfb8aa3b, v28
	v_mul_f32_e32 v32, 0xbfb8aa3b, v30
	v_mul_f32_e32 v33, 0xbfb8aa3b, v31
	v_mul_f32_e32 v35, 0xbfb8aa3b, v29
	v_exp_f32_e32 v32, v32
	v_exp_f32_e32 v33, v33
	v_exp_f32_e32 v34, v34
	v_exp_f32_e32 v35, v35
	v_add_f32_e32 v32, 1.0, v32
	v_add_f32_e32 v33, 1.0, v33
	v_add_f32_e32 v34, 1.0, v34
	v_add_f32_e32 v35, 1.0, v35
	v_rcp_f32_e32 v32, v32
	v_rcp_f32_e32 v33, v33
	v_rcp_f32_e32 v34, v34
	v_rcp_f32_e32 v35, v35
	v_pk_mul_f32 v[22:23], v[22:23], v[142:143] op_sel_hi:[1,0]
	v_pk_mul_f32 v[20:21], v[20:21], v[142:143] op_sel_hi:[1,0]
	v_pk_mul_f32 v[30:31], v[30:31], v[32:33]
	v_pk_mul_f32 v[28:29], v[28:29], v[34:35]
	v_pk_mul_f32 v[20:21], v[20:21], v[30:31]
	v_pk_mul_f32 v[22:23], v[22:23], v[28:29]
	v_cvt_pk_bf16_f32 v20, v20, v21
	v_cvt_pk_bf16_f32 v21, v22, v23
	v_pk_mul_f32 v[22:23], v[26:27], v[142:143] op_sel_hi:[1,0]
	v_pk_mul_f32 v[24:25], v[24:25], v[142:143] op_sel_hi:[1,0]
	v_mul_f32_e32 v28, 0xbfb8aa3b, v22
	v_mul_f32_e32 v26, 0xbfb8aa3b, v24
	v_mul_f32_e32 v27, 0xbfb8aa3b, v25
	v_mul_f32_e32 v29, 0xbfb8aa3b, v23
	v_exp_f32_e32 v26, v26
	v_exp_f32_e32 v27, v27
	v_exp_f32_e32 v28, v28
	v_exp_f32_e32 v29, v29
	v_add_f32_e32 v26, 1.0, v26
	v_add_f32_e32 v27, 1.0, v27
	v_add_f32_e32 v28, 1.0, v28
	v_add_f32_e32 v29, 1.0, v29
	v_rcp_f32_e32 v26, v26
	v_rcp_f32_e32 v27, v27
	v_rcp_f32_e32 v28, v28
	v_rcp_f32_e32 v29, v29
	v_pk_mul_f32 v[14:15], v[14:15], v[142:143] op_sel_hi:[1,0]
	v_pk_mul_f32 v[12:13], v[12:13], v[142:143] op_sel_hi:[1,0]
	v_pk_mul_f32 v[24:25], v[24:25], v[26:27]
	v_pk_mul_f32 v[22:23], v[22:23], v[28:29]
	v_pk_mul_f32 v[12:13], v[12:13], v[24:25]
	v_pk_mul_f32 v[14:15], v[14:15], v[22:23]
	ds_bpermute_b32 v20, v149, v20
	ds_bpermute_b32 v21, v149, v21
	v_cvt_pk_bf16_f32 v12, v12, v13
	v_cvt_pk_bf16_f32 v13, v14, v15
	ds_bpermute_b32 v12, v149, v12
	ds_bpermute_b32 v13, v149, v13
	v_add_u32_e32 v36, 0xa0, v151
	v_mad_i64_i32 v[14:15], s[22:23], v36, s47, v[136:137]
	v_lshl_add_u64 v[14:15], v[14:15], 0, v[140:141]
	s_waitcnt lgkmcnt(2)
	global_store_dwordx2 v[14:15], v[20:21], off
	s_waitcnt lgkmcnt(0)
	global_store_dwordx2 v[14:15], v[12:13], off offset:32
	v_pk_mul_f32 v[12:13], v[18:19], v[138:139] op_sel_hi:[1,0]
	v_pk_mul_f32 v[14:15], v[16:17], v[138:139] op_sel_hi:[1,0]
	v_mul_f32_e32 v18, 0xbfb8aa3b, v12
	v_mul_f32_e32 v16, 0xbfb8aa3b, v14
	v_mul_f32_e32 v17, 0xbfb8aa3b, v15
	v_mul_f32_e32 v19, 0xbfb8aa3b, v13
	v_exp_f32_e32 v16, v16
	v_exp_f32_e32 v17, v17
	v_exp_f32_e32 v18, v18
	v_exp_f32_e32 v19, v19
	v_add_f32_e32 v16, 1.0, v16
	v_add_f32_e32 v17, 1.0, v17
	v_add_f32_e32 v18, 1.0, v18
	v_add_f32_e32 v19, 1.0, v19
	v_rcp_f32_e32 v16, v16
	v_rcp_f32_e32 v17, v17
	v_rcp_f32_e32 v18, v18
	v_rcp_f32_e32 v19, v19
	v_pk_mul_f32 v[6:7], v[6:7], v[138:139] op_sel_hi:[1,0]
	v_pk_mul_f32 v[4:5], v[4:5], v[138:139] op_sel_hi:[1,0]
	v_pk_mul_f32 v[14:15], v[14:15], v[16:17]
	v_pk_mul_f32 v[12:13], v[12:13], v[18:19]
	v_pk_mul_f32 v[4:5], v[4:5], v[14:15]
	v_pk_mul_f32 v[6:7], v[6:7], v[12:13]
	v_cvt_pk_bf16_f32 v4, v4, v5
	v_cvt_pk_bf16_f32 v5, v6, v7
	v_pk_mul_f32 v[6:7], v[10:11], v[138:139] op_sel_hi:[1,0]
	v_pk_mul_f32 v[8:9], v[8:9], v[138:139] op_sel_hi:[1,0]
	v_mul_f32_e32 v12, 0xbfb8aa3b, v6
	v_mul_f32_e32 v10, 0xbfb8aa3b, v8
	v_mul_f32_e32 v11, 0xbfb8aa3b, v9
	v_mul_f32_e32 v13, 0xbfb8aa3b, v7
	v_exp_f32_e32 v10, v10
	v_exp_f32_e32 v11, v11
	v_exp_f32_e32 v12, v12
	v_exp_f32_e32 v13, v13
	v_add_f32_e32 v10, 1.0, v10
	v_add_f32_e32 v11, 1.0, v11
	v_add_f32_e32 v12, 1.0, v12
	v_add_f32_e32 v13, 1.0, v13
	v_rcp_f32_e32 v10, v10
	v_rcp_f32_e32 v11, v11
	v_rcp_f32_e32 v12, v12
	v_rcp_f32_e32 v13, v13
	v_pk_mul_f32 v[2:3], v[2:3], v[138:139] op_sel_hi:[1,0]
	v_pk_mul_f32 v[0:1], v[0:1], v[138:139] op_sel_hi:[1,0]
	v_pk_mul_f32 v[8:9], v[8:9], v[10:11]
	v_pk_mul_f32 v[6:7], v[6:7], v[12:13]
	v_pk_mul_f32 v[0:1], v[0:1], v[8:9]
	v_pk_mul_f32 v[2:3], v[2:3], v[6:7]
	ds_bpermute_b32 v4, v149, v4
	ds_bpermute_b32 v5, v149, v5
	v_cvt_pk_bf16_f32 v0, v0, v1
	v_cvt_pk_bf16_f32 v1, v2, v3
	ds_bpermute_b32 v0, v149, v0
	ds_bpermute_b32 v1, v149, v1
	v_add_u32_e32 v20, 0xb0, v151
	v_mad_i64_i32 v[2:3], s[22:23], v20, s47, v[136:137]
	v_lshl_add_u64 v[2:3], v[2:3], 0, v[140:141]
	s_mov_b64 s[22:23], s[16:17]
	s_waitcnt lgkmcnt(2)
	global_store_dwordx2 v[2:3], v[4:5], off
	s_waitcnt lgkmcnt(0)
	global_store_dwordx2 v[2:3], v[0:1], off offset:32
	s_cbranch_vccz .LBB0_1164
	s_waitcnt vmcnt(0)
	s_cmpk_gt_u32 s28, 0xff
	s_cbranch_scc1 .LBB0_1171
	s_barrier

.LBB0_1258:
	ds_read_b128 v[128:131], v159
	ds_read_b128 v[132:135], v159 offset:1024
	ds_read_b128 v[136:139], v159 offset:2048
	ds_read_b128 v[150:153], v159 offset:3072
	s_add_i32 s54, s18, 2
	s_add_u32 s19, s16, 0xffea0080
	s_addc_u32 s20, s17, -1
	s_cmp_eq_u32 s13, s18
	s_cselect_b32 s18, s4, s52
	s_cselect_b32 s21, s15, s20
	s_cselect_b32 s20, s14, s19
	s_cselect_b32 s19, s5, s53

	s_add_i32 m0, s26, 0xc000
	ds_read_b128 v[154:157], v160
	ds_read_b128 v[162:165], v160 offset:1024
	ds_read_b128 v[172:175], v160 offset:2048
	ds_read_b128 v[176:179], v160 offset:3072
	ds_read_b128 v[180:183], v160 offset:4096
	ds_read_b128 v[184:187], v160 offset:5120
	ds_read_b128 v[188:191], v160 offset:6144
	ds_read_b128 v[192:195], v160 offset:7168
	global_load_lds_dwordx4 v146, s[16:17]
	s_add_i32 m0, s26, 0xe000
	s_nop 0

	global_load_lds_dwordx4 v148, s[16:17]
	s_waitcnt lgkmcnt(8)
	s_barrier
	s_waitcnt lgkmcnt(0)


	v_mfma_f32_16x16x32_bf16 v[124:127], v[128:131], v[154:157], v[124:127]
	v_mfma_f32_16x16x32_bf16 v[120:123], v[136:139], v[154:157], v[120:123]
	v_mfma_f32_16x16x32_bf16 v[116:119], v[128:131], v[172:175], v[116:119]
	v_mfma_f32_16x16x32_bf16 v[104:107], v[136:139], v[172:175], v[104:107]
	v_mfma_f32_16x16x32_bf16 v[96:99], v[128:131], v[180:183], v[96:99]
	v_mfma_f32_16x16x32_bf16 v[88:91], v[136:139], v[180:183], v[88:91]
	v_mfma_f32_16x16x32_bf16 v[80:83], v[128:131], v[188:191], v[80:83]
	v_mfma_f32_16x16x32_bf16 v[72:75], v[136:139], v[188:191], v[72:75]
	v_mfma_f32_16x16x32_bf16 v[124:127], v[132:135], v[162:165], v[124:127]
	v_mfma_f32_16x16x32_bf16 v[120:123], v[150:153], v[162:165], v[120:123]
	v_mfma_f32_16x16x32_bf16 v[116:119], v[132:135], v[176:179], v[116:119]
	v_mfma_f32_16x16x32_bf16 v[104:107], v[150:153], v[176:179], v[104:107]
	v_mfma_f32_16x16x32_bf16 v[96:99], v[132:135], v[184:187], v[96:99]
	v_mfma_f32_16x16x32_bf16 v[88:91], v[150:153], v[184:187], v[88:91]
	v_mfma_f32_16x16x32_bf16 v[80:83], v[132:135], v[192:195], v[80:83]
	v_mfma_f32_16x16x32_bf16 v[72:75], v[150:153], v[192:195], v[72:75]

	s_barrier
	s_add_i32 s55, s35, s25
	v_lshl_add_u64 v[166:167], s[18:19], 0, v[140:141]
	s_mov_b32 m0, s55
	ds_read_b128 v[196:199], v161
	ds_read_b128 v[200:203], v161 offset:1024
	ds_read_b128 v[204:207], v161 offset:2048
	ds_read_b128 v[212:215], v161 offset:3072
	global_load_lds_dwordx4 v[166:167], off
	s_add_i32 m0, s55, 0x2000
	v_lshl_add_u64 v[208:209], s[18:19], 0, v[142:143]

	global_load_lds_dwordx4 v[208:209], off
	s_barrier
	s_waitcnt lgkmcnt(0)


	v_mfma_f32_16x16x32_bf16 v[112:115], v[196:199], v[154:157], v[112:115]
	v_mfma_f32_16x16x32_bf16 v[108:111], v[204:207], v[154:157], v[108:111]
	v_mfma_f32_16x16x32_bf16 v[100:103], v[196:199], v[172:175], v[100:103]
	v_mfma_f32_16x16x32_bf16 v[92:95], v[204:207], v[172:175], v[92:95]
	v_mfma_f32_16x16x32_bf16 v[84:87], v[196:199], v[180:183], v[84:87]
	v_mfma_f32_16x16x32_bf16 v[76:79], v[204:207], v[180:183], v[76:79]
	v_mfma_f32_16x16x32_bf16 v[68:71], v[196:199], v[188:191], v[68:71]
	v_mfma_f32_16x16x32_bf16 v[64:67], v[204:207], v[188:191], v[64:67]
	v_mfma_f32_16x16x32_bf16 v[112:115], v[200:203], v[162:165], v[112:115]
	v_mfma_f32_16x16x32_bf16 v[108:111], v[212:215], v[162:165], v[108:111]
	v_mfma_f32_16x16x32_bf16 v[100:103], v[200:203], v[176:179], v[100:103]
	v_mfma_f32_16x16x32_bf16 v[92:95], v[212:215], v[176:179], v[92:95]
	v_mfma_f32_16x16x32_bf16 v[84:87], v[200:203], v[184:187], v[84:87]
	v_mfma_f32_16x16x32_bf16 v[76:79], v[212:215], v[184:187], v[76:79]
	v_mfma_f32_16x16x32_bf16 v[68:71], v[200:203], v[192:195], v[68:71]
	v_mfma_f32_16x16x32_bf16 v[64:67], v[212:215], v[192:195], v[64:67]

	s_mov_b32 m0, s26
	v_lshl_add_u64 v[216:217], s[20:21], 0, v[140:141]
	s_barrier
	ds_read_b128 v[154:157], v160 offset:16384
	ds_read_b128 v[162:165], v160 offset:17408
	ds_read_b128 v[172:175], v160 offset:18432
	ds_read_b128 v[176:179], v160 offset:19456
	ds_read_b128 v[180:183], v160 offset:20480
	ds_read_b128 v[184:187], v160 offset:21504
	ds_read_b128 v[188:191], v160 offset:22528
	ds_read_b128 v[192:195], v160 offset:23552
	global_load_lds_dwordx4 v[216:217], off
	s_mov_b32 m0, s27
	v_lshl_add_u64 v[218:219], s[20:21], 0, v[142:143]

	global_load_lds_dwordx4 v[218:219], off
	s_barrier
	s_waitcnt lgkmcnt(0)


	v_mfma_f32_16x16x32_bf16 v[60:63], v[128:131], v[154:157], v[60:63]
	v_mfma_f32_16x16x32_bf16 v[56:59], v[136:139], v[154:157], v[56:59]
	v_mfma_f32_16x16x32_bf16 v[52:55], v[128:131], v[172:175], v[52:55]
	v_mfma_f32_16x16x32_bf16 v[40:43], v[136:139], v[172:175], v[40:43]
	v_mfma_f32_16x16x32_bf16 v[36:39], v[128:131], v[180:183], v[36:39]
	v_mfma_f32_16x16x32_bf16 v[24:27], v[136:139], v[180:183], v[24:27]
	v_mfma_f32_16x16x32_bf16 v[20:23], v[128:131], v[188:191], v[20:23]
	v_mfma_f32_16x16x32_bf16 v[8:11], v[136:139], v[188:191], v[8:11]
	v_mfma_f32_16x16x32_bf16 v[60:63], v[132:135], v[162:165], v[60:63]
	v_mfma_f32_16x16x32_bf16 v[56:59], v[150:153], v[162:165], v[56:59]
	v_mfma_f32_16x16x32_bf16 v[52:55], v[132:135], v[176:179], v[52:55]
	v_mfma_f32_16x16x32_bf16 v[40:43], v[150:153], v[176:179], v[40:43]
	v_mfma_f32_16x16x32_bf16 v[36:39], v[132:135], v[184:187], v[36:39]
	v_mfma_f32_16x16x32_bf16 v[24:27], v[150:153], v[184:187], v[24:27]
	v_mfma_f32_16x16x32_bf16 v[20:23], v[132:135], v[192:195], v[20:23]
	v_mfma_f32_16x16x32_bf16 v[8:11], v[150:153], v[192:195], v[8:11]

	s_barrier
	s_add_u32 s56, s18, 0x160000
	s_addc_u32 s57, s19, 0
	s_add_i32 s55, s36, s25
	s_mov_b32 m0, s55
	s_nop 0

	global_load_lds_dwordx4 v140, s[56:57]
	s_add_i32 m0, s55, 0x2000
	s_nop 0

	global_load_lds_dwordx4 v142, s[56:57]
	s_waitcnt vmcnt(6)
	s_barrier

	v_mfma_f32_16x16x32_bf16 v[48:51], v[196:199], v[154:157], v[48:51]
	v_mfma_f32_16x16x32_bf16 v[44:47], v[204:207], v[154:157], v[44:47]
	v_mfma_f32_16x16x32_bf16 v[32:35], v[196:199], v[172:175], v[32:35]
	v_mfma_f32_16x16x32_bf16 v[28:31], v[204:207], v[172:175], v[28:31]
	v_mfma_f32_16x16x32_bf16 v[16:19], v[196:199], v[180:183], v[16:19]
	v_mfma_f32_16x16x32_bf16 v[12:15], v[204:207], v[180:183], v[12:15]
	v_mfma_f32_16x16x32_bf16 v[4:7], v[196:199], v[188:191], v[4:7]
	v_mfma_f32_16x16x32_bf16 v[0:3], v[204:207], v[188:191], v[0:3]
	v_mfma_f32_16x16x32_bf16 v[48:51], v[200:203], v[162:165], v[48:51]
	v_mfma_f32_16x16x32_bf16 v[44:47], v[212:215], v[162:165], v[44:47]
	v_mfma_f32_16x16x32_bf16 v[32:35], v[200:203], v[176:179], v[32:35]
	v_mfma_f32_16x16x32_bf16 v[28:31], v[212:215], v[176:179], v[28:31]
	v_mfma_f32_16x16x32_bf16 v[16:19], v[200:203], v[184:187], v[16:19]
	v_mfma_f32_16x16x32_bf16 v[12:15], v[212:215], v[184:187], v[12:15]
	v_mfma_f32_16x16x32_bf16 v[4:7], v[200:203], v[192:195], v[4:7]
	v_mfma_f32_16x16x32_bf16 v[0:3], v[212:215], v[192:195], v[0:3]

	s_add_i32 s55, 0, 0x18000
	v_add_u32_e32 v144, s55, v158
	s_barrier
	ds_read_b128 v[128:131], v144
	ds_read_b128 v[132:135], v144 offset:1024
	ds_read_b128 v[136:139], v144 offset:2048
	ds_read_b128 v[150:153], v144 offset:3072
	s_add_u32 s20, s20, 0x160000
	s_addc_u32 s21, s21, 0
	s_mov_b32 m0, s28

	ds_read_b128 v[154:157], v160 offset:32768
	ds_read_b128 v[162:165], v160 offset:33792
	ds_read_b128 v[172:175], v160 offset:34816
	ds_read_b128 v[176:179], v160 offset:35840
	ds_read_b128 v[180:183], v160 offset:36864
	ds_read_b128 v[184:187], v160 offset:37888
	ds_read_b128 v[188:191], v160 offset:38912
	ds_read_b128 v[192:195], v160 offset:39936
	global_load_lds_dwordx4 v140, s[20:21]
	s_mov_b32 m0, s29
	s_nop 0

	global_load_lds_dwordx4 v142, s[20:21]
	s_waitcnt lgkmcnt(8)
	s_barrier
	s_waitcnt lgkmcnt(0)


	v_mfma_f32_16x16x32_bf16 v[124:127], v[128:131], v[154:157], v[124:127]
	v_mfma_f32_16x16x32_bf16 v[120:123], v[136:139], v[154:157], v[120:123]
	v_mfma_f32_16x16x32_bf16 v[116:119], v[128:131], v[172:175], v[116:119]
	v_mfma_f32_16x16x32_bf16 v[104:107], v[136:139], v[172:175], v[104:107]
	v_mfma_f32_16x16x32_bf16 v[96:99], v[128:131], v[180:183], v[96:99]
	v_mfma_f32_16x16x32_bf16 v[88:91], v[136:139], v[180:183], v[88:91]
	v_mfma_f32_16x16x32_bf16 v[80:83], v[128:131], v[188:191], v[80:83]
	v_mfma_f32_16x16x32_bf16 v[72:75], v[136:139], v[188:191], v[72:75]
	v_mfma_f32_16x16x32_bf16 v[124:127], v[132:135], v[162:165], v[124:127]
	v_mfma_f32_16x16x32_bf16 v[120:123], v[150:153], v[162:165], v[120:123]
	v_mfma_f32_16x16x32_bf16 v[116:119], v[132:135], v[176:179], v[116:119]
	v_mfma_f32_16x16x32_bf16 v[104:107], v[150:153], v[176:179], v[104:107]
	v_mfma_f32_16x16x32_bf16 v[96:99], v[132:135], v[184:187], v[96:99]
	v_mfma_f32_16x16x32_bf16 v[88:91], v[150:153], v[184:187], v[88:91]
	v_mfma_f32_16x16x32_bf16 v[80:83], v[132:135], v[192:195], v[80:83]
	v_mfma_f32_16x16x32_bf16 v[72:75], v[150:153], v[192:195], v[72:75]

	s_barrier
	s_add_i32 s20, 0, 0x1c000
	s_add_i32 s21, s55, s25
	v_add_u32_e32 v144, s20, v158
	v_lshl_add_u64 v[166:167], v[166:167], 0, s[6:7]
	s_mov_b32 m0, s21
	ds_read_b128 v[196:199], v144
	ds_read_b128 v[200:203], v144 offset:1024
	ds_read_b128 v[204:207], v144 offset:2048
	ds_read_b128 v[212:215], v144 offset:3072
	global_load_lds_dwordx4 v[166:167], off
	s_add_i32 m0, s21, 0x2000
	v_lshl_add_u64 v[166:167], v[208:209], 0, s[6:7]

	global_load_lds_dwordx4 v[166:167], off
	s_barrier
	s_waitcnt lgkmcnt(0)


	v_mfma_f32_16x16x32_bf16 v[112:115], v[196:199], v[154:157], v[112:115]
	v_mfma_f32_16x16x32_bf16 v[108:111], v[204:207], v[154:157], v[108:111]
	v_mfma_f32_16x16x32_bf16 v[100:103], v[196:199], v[172:175], v[100:103]
	v_mfma_f32_16x16x32_bf16 v[92:95], v[204:207], v[172:175], v[92:95]
	v_mfma_f32_16x16x32_bf16 v[84:87], v[196:199], v[180:183], v[84:87]
	v_mfma_f32_16x16x32_bf16 v[76:79], v[204:207], v[180:183], v[76:79]
	v_mfma_f32_16x16x32_bf16 v[68:71], v[196:199], v[188:191], v[68:71]
	v_mfma_f32_16x16x32_bf16 v[64:67], v[204:207], v[188:191], v[64:67]
	v_mfma_f32_16x16x32_bf16 v[112:115], v[200:203], v[162:165], v[112:115]
	v_mfma_f32_16x16x32_bf16 v[108:111], v[212:215], v[162:165], v[108:111]
	v_mfma_f32_16x16x32_bf16 v[100:103], v[200:203], v[176:179], v[100:103]
	v_mfma_f32_16x16x32_bf16 v[92:95], v[212:215], v[176:179], v[92:95]
	v_mfma_f32_16x16x32_bf16 v[84:87], v[200:203], v[184:187], v[84:87]
	v_mfma_f32_16x16x32_bf16 v[76:79], v[212:215], v[184:187], v[76:79]
	v_mfma_f32_16x16x32_bf16 v[68:71], v[200:203], v[192:195], v[68:71]
	v_mfma_f32_16x16x32_bf16 v[64:67], v[212:215], v[192:195], v[64:67]

	s_mov_b32 m0, s33
	v_lshl_add_u64 v[166:167], v[216:217], 0, s[6:7]
	s_barrier
	ds_read_b128 v[154:157], v160 offset:49152
	ds_read_b128 v[162:165], v160 offset:50176
	ds_read_b128 v[172:175], v160 offset:51200
	ds_read_b128 v[176:179], v160 offset:52224
	ds_read_b128 v[180:183], v160 offset:53248
	ds_read_b128 v[184:187], v160 offset:54272
	ds_read_b128 v[188:191], v160 offset:55296
	ds_read_b128 v[192:195], v160 offset:56320
	global_load_lds_dwordx4 v[166:167], off
	s_mov_b32 m0, s34
	v_lshl_add_u64 v[166:167], v[218:219], 0, s[6:7]

	global_load_lds_dwordx4 v[166:167], off
	s_barrier
	s_waitcnt lgkmcnt(0)


	v_mfma_f32_16x16x32_bf16 v[60:63], v[128:131], v[154:157], v[60:63]
	v_mfma_f32_16x16x32_bf16 v[56:59], v[136:139], v[154:157], v[56:59]
	v_mfma_f32_16x16x32_bf16 v[52:55], v[128:131], v[172:175], v[52:55]
	v_mfma_f32_16x16x32_bf16 v[40:43], v[136:139], v[172:175], v[40:43]
	v_mfma_f32_16x16x32_bf16 v[36:39], v[128:131], v[180:183], v[36:39]
	v_mfma_f32_16x16x32_bf16 v[24:27], v[136:139], v[180:183], v[24:27]
	v_mfma_f32_16x16x32_bf16 v[20:23], v[128:131], v[188:191], v[20:23]
	v_mfma_f32_16x16x32_bf16 v[8:11], v[136:139], v[188:191], v[8:11]
	v_mfma_f32_16x16x32_bf16 v[60:63], v[132:135], v[162:165], v[60:63]
	v_mfma_f32_16x16x32_bf16 v[56:59], v[150:153], v[162:165], v[56:59]
	v_mfma_f32_16x16x32_bf16 v[52:55], v[132:135], v[176:179], v[52:55]
	v_mfma_f32_16x16x32_bf16 v[40:43], v[150:153], v[176:179], v[40:43]
	v_mfma_f32_16x16x32_bf16 v[36:39], v[132:135], v[184:187], v[36:39]
	v_mfma_f32_16x16x32_bf16 v[24:27], v[150:153], v[184:187], v[24:27]
	v_mfma_f32_16x16x32_bf16 v[20:23], v[132:135], v[192:195], v[20:23]
	v_mfma_f32_16x16x32_bf16 v[8:11], v[150:153], v[192:195], v[8:11]

	s_barrier
	s_add_u32 s18, s18, 0x160080
	s_addc_u32 s19, s19, 0
	s_add_i32 s20, s20, s25
	s_mov_b32 m0, s20
	s_nop 0

	global_load_lds_dwordx4 v140, s[18:19]
	s_add_i32 m0, s20, 0x2000
	s_nop 0

	global_load_lds_dwordx4 v142, s[18:19]
	s_waitcnt vmcnt(6)
	s_barrier

	v_mfma_f32_16x16x32_bf16 v[48:51], v[196:199], v[154:157], v[48:51]
	v_mfma_f32_16x16x32_bf16 v[44:47], v[204:207], v[154:157], v[44:47]
	v_mfma_f32_16x16x32_bf16 v[32:35], v[196:199], v[172:175], v[32:35]
	v_mfma_f32_16x16x32_bf16 v[28:31], v[204:207], v[172:175], v[28:31]
	v_mfma_f32_16x16x32_bf16 v[16:19], v[196:199], v[180:183], v[16:19]
	v_mfma_f32_16x16x32_bf16 v[12:15], v[204:207], v[180:183], v[12:15]
	v_mfma_f32_16x16x32_bf16 v[4:7], v[196:199], v[188:191], v[4:7]
	v_mfma_f32_16x16x32_bf16 v[0:3], v[204:207], v[188:191], v[0:3]
	v_mfma_f32_16x16x32_bf16 v[48:51], v[200:203], v[162:165], v[48:51]
	v_mfma_f32_16x16x32_bf16 v[44:47], v[212:215], v[162:165], v[44:47]
	v_mfma_f32_16x16x32_bf16 v[32:35], v[200:203], v[176:179], v[32:35]
	v_mfma_f32_16x16x32_bf16 v[28:31], v[212:215], v[176:179], v[28:31]
	v_mfma_f32_16x16x32_bf16 v[16:19], v[200:203], v[184:187], v[16:19]
	v_mfma_f32_16x16x32_bf16 v[12:15], v[212:215], v[184:187], v[12:15]
	v_mfma_f32_16x16x32_bf16 v[4:7], v[200:203], v[192:195], v[4:7]
	v_mfma_f32_16x16x32_bf16 v[0:3], v[212:215], v[192:195], v[0:3]

	s_add_u32 s16, s16, 0x100
	s_addc_u32 s17, s17, 0
	s_add_u32 s52, s52, 0x100
	s_addc_u32 s53, s53, 0
	s_cmp_ge_i32 s54, s51
	s_mov_b32 s18, s54
	s_barrier
	s_cbranch_scc0 .LBB0_1258
	v_mov_b32_e32 v128, v210
	v_mov_b32_e32 v129, v169
	s_mov_b64 s[16:17], -1
	v_lshl_add_u32 v128, v128, 4, v129
	v_ashrrev_i32_e32 v150, 2, v128
	v_and_b32_e32 v129, 3, v129
	v_and_b32_e32 v128, -4, v128
	v_lshl_add_u32 v162, v129, 6, v128
	s_cmp_lt_i32 s2, 0
	v_lshlrev_b32_e32 v144, 4, v129
	s_cbranch_scc0 .LBB0_1261
	s_lshl_b32 s13, s50, 8
	s_add_i32 s13, s13, s30
	v_add_u32_e32 v128, s13, v150
	v_ashrrev_i32_e32 v129, 31, v128
	v_readlane_b32 s52, v254, 22
	v_lshlrev_b64 v[128:129], 13, v[128:129]
	v_readlane_b32 s66, v254, 36
	v_readlane_b32 s67, v254, 37
	s_lshl_b32 s16, s49, 8
	s_ashr_i32 s17, s16, 31
	v_lshl_add_u64 v[128:129], s[66:67], 0, v[128:129]
	v_lshl_add_u64 v[128:129], s[16:17], 2, v[128:129]
	s_lshl_b32 s16, s31, 2
	s_mov_b32 s17, s3
	v_lshl_add_u64 v[128:129], v[128:129], 0, s[16:17]
	v_lshl_add_u64 v[152:153], v[128:129], 0, v[144:145]
	global_load_dwordx4 v[164:167], v[152:153], off
	global_load_dwordx4 v[172:175], v[152:153], off offset:64
	global_load_dwordx4 v[176:179], v[152:153], off offset:512
	global_load_dwordx4 v[180:183], v[152:153], off offset:576
	v_add_co_u32_e32 v136, vcc, s37, v152
	ds_bpermute_b32 v138, v162, v124
	s_nop 0
	v_addc_co_u32_e32 v137, vcc, 0, v153, vcc
	global_load_dwordx4 v[184:187], v[136:137], off
	global_load_dwordx4 v[188:191], v[136:137], off offset:64
	global_load_dwordx4 v[192:195], v[136:137], off offset:512
	global_load_dwordx4 v[132:135], v[136:137], off offset:576
	v_add_co_u32_e32 v208, vcc, s38, v152
	ds_bpermute_b32 v139, v162, v125
	s_nop 0
	v_addc_co_u32_e32 v209, vcc, 0, v153, vcc
	global_load_dwordx4 v[196:199], v[208:209], off
	global_load_dwordx4 v[200:203], v[208:209], off offset:64
	global_load_dwordx4 v[204:207], v[208:209], off offset:512
	global_load_dwordx4 v[212:215], v[208:209], off offset:576
	v_add_co_u32_e32 v154, vcc, s39, v152
	ds_bpermute_b32 v156, v162, v126
	s_nop 0
	v_addc_co_u32_e32 v155, vcc, 0, v153, vcc
	global_load_dwordx4 v[216:219], v[154:155], off
	global_load_dwordx4 v[220:223], v[154:155], off offset:64
	global_load_dwordx4 v[224:227], v[154:155], off offset:512
	global_load_dwordx4 v[128:131], v[154:155], off offset:576
	ds_bpermute_b32 v157, v162, v127
	ds_bpermute_b32 v228, v162, v120
	ds_bpermute_b32 v229, v162, v121
	ds_bpermute_b32 v230, v162, v122
	ds_bpermute_b32 v231, v162, v123
	ds_bpermute_b32 v232, v162, v112
	ds_bpermute_b32 v233, v162, v113
	ds_bpermute_b32 v234, v162, v114
	ds_bpermute_b32 v235, v162, v115
	ds_bpermute_b32 v236, v162, v108
	ds_bpermute_b32 v237, v162, v109
	ds_bpermute_b32 v238, v162, v110
	ds_bpermute_b32 v239, v162, v111
	ds_bpermute_b32 v240, v162, v116
	ds_bpermute_b32 v241, v162, v117
	ds_bpermute_b32 v242, v162, v118
	ds_bpermute_b32 v243, v162, v119
	ds_bpermute_b32 v244, v162, v104
	ds_bpermute_b32 v245, v162, v105
	ds_bpermute_b32 v246, v162, v106
	ds_bpermute_b32 v247, v162, v107
	ds_bpermute_b32 v248, v162, v100
	ds_bpermute_b32 v249, v162, v101
	ds_bpermute_b32 v250, v162, v102
	ds_bpermute_b32 v251, v162, v103
	ds_bpermute_b32 v252, v162, v94
	ds_bpermute_b32 v253, v162, v95
	v_readlane_b32 s53, v254, 23
	v_readlane_b32 s54, v254, 24
	v_readlane_b32 s55, v254, 25
	v_readlane_b32 s56, v254, 26
	v_readlane_b32 s57, v254, 27
	v_readlane_b32 s58, v254, 28
	v_readlane_b32 s59, v254, 29
	v_readlane_b32 s60, v254, 30
	v_readlane_b32 s61, v254, 31
	v_readlane_b32 s62, v254, 32
	v_readlane_b32 s63, v254, 33
	v_readlane_b32 s64, v254, 34
	v_readlane_b32 s65, v254, 35
	s_mov_b64 s[16:17], 0
	s_waitcnt vmcnt(0) lgkmcnt(0)
	v_pk_add_f32 v[164:165], v[164:165], v[138:139]
	ds_bpermute_b32 v138, v162, v92
	ds_bpermute_b32 v139, v162, v93
	v_pk_add_f32 v[166:167], v[166:167], v[156:157]
	v_pk_add_f32 v[172:173], v[172:173], v[228:229]
	v_pk_add_f32 v[174:175], v[174:175], v[230:231]
	v_pk_add_f32 v[178:179], v[178:179], v[234:235]
	v_pk_add_f32 v[176:177], v[176:177], v[232:233]
	v_pk_add_f32 v[182:183], v[182:183], v[238:239]
	v_pk_add_f32 v[180:181], v[180:181], v[236:237]
	global_store_dwordx4 v[152:153], v[164:167], off
	global_store_dwordx4 v[152:153], v[172:175], off offset:64
	global_store_dwordx4 v[152:153], v[176:179], off offset:512
	global_store_dwordx4 v[152:153], v[180:183], off offset:576
	v_pk_add_f32 v[166:167], v[186:187], v[242:243]
	v_pk_add_f32 v[164:165], v[184:185], v[240:241]
	v_pk_add_f32 v[172:173], v[188:189], v[244:245]
	v_add_co_u32_e32 v156, vcc, s40, v152
	v_pk_add_f32 v[174:175], v[190:191], v[246:247]
	v_pk_add_f32 v[178:179], v[194:195], v[250:251]
	v_pk_add_f32 v[176:177], v[192:193], v[248:249]
	global_store_dwordx4 v[136:137], v[164:167], off
	global_store_dwordx4 v[136:137], v[172:175], off offset:64
	global_store_dwordx4 v[136:137], v[176:179], off offset:512
	v_addc_co_u32_e32 v157, vcc, 0, v153, vcc
	ds_bpermute_b32 v172, v162, v98
	ds_bpermute_b32 v173, v162, v99
	v_pk_add_f32 v[134:135], v[134:135], v[252:253]
	global_load_dwordx4 v[164:167], v[156:157], off
	s_waitcnt lgkmcnt(2)
	v_pk_add_f32 v[132:133], v[132:133], v[138:139]
	global_store_dwordx4 v[136:137], v[132:135], off offset:576
	ds_bpermute_b32 v132, v162, v96
	ds_bpermute_b32 v133, v162, v97
	ds_bpermute_b32 v136, v162, v90
	ds_bpermute_b32 v137, v162, v91
	ds_bpermute_b32 v138, v162, v88
	ds_bpermute_b32 v139, v162, v89
	s_waitcnt lgkmcnt(6)
	v_pk_add_f32 v[134:135], v[198:199], v[172:173]
	global_load_dwordx4 v[172:175], v[156:157], off offset:64
	s_waitcnt lgkmcnt(4)
	v_pk_add_f32 v[132:133], v[196:197], v[132:133]
	global_store_dwordx4 v[208:209], v[132:135], off
	ds_bpermute_b32 v180, v162, v76
	ds_bpermute_b32 v182, v162, v78
	s_waitcnt lgkmcnt(4)
	v_pk_add_f32 v[134:135], v[202:203], v[136:137]
	ds_bpermute_b32 v136, v162, v86
	ds_bpermute_b32 v137, v162, v87
	s_waitcnt lgkmcnt(4)
	v_pk_add_f32 v[132:133], v[200:201], v[138:139]
	ds_bpermute_b32 v138, v162, v84
	ds_bpermute_b32 v139, v162, v85
	global_store_dwordx4 v[208:209], v[132:135], off offset:64
	global_load_dwordx4 v[132:135], v[156:157], off offset:512
	s_waitcnt lgkmcnt(2)
	v_pk_add_f32 v[178:179], v[206:207], v[136:137]
	ds_bpermute_b32 v183, v162, v79
	s_waitcnt lgkmcnt(1)
	v_pk_add_f32 v[176:177], v[204:205], v[138:139]
	global_load_dwordx4 v[136:139], v[156:157], off offset:576
	ds_bpermute_b32 v181, v162, v77
	global_store_dwordx4 v[208:209], v[176:179], off offset:512
	v_add_co_u32_e32 v204, vcc, s41, v152
	s_waitcnt lgkmcnt(1)
	v_pk_add_f32 v[178:179], v[214:215], v[182:183]
	s_waitcnt lgkmcnt(0)
	v_pk_add_f32 v[176:177], v[212:213], v[180:181]
	ds_bpermute_b32 v180, v162, v80
	ds_bpermute_b32 v181, v162, v81
	ds_bpermute_b32 v182, v162, v82
	ds_bpermute_b32 v183, v162, v83
	v_addc_co_u32_e32 v205, vcc, 0, v153, vcc
	global_store_dwordx4 v[208:209], v[176:179], off offset:576
	global_load_dwordx4 v[176:179], v[204:205], off
	s_waitcnt lgkmcnt(0)
	v_pk_add_f32 v[182:183], v[218:219], v[182:183]
	global_load_dwordx4 v[184:187], v[204:205], off offset:64
	v_pk_add_f32 v[180:181], v[216:217], v[180:181]
	ds_bpermute_b32 v188, v162, v74
	ds_bpermute_b32 v189, v162, v75
	global_store_dwordx4 v[154:155], v[180:183], off
	ds_bpermute_b32 v180, v162, v72
	ds_bpermute_b32 v181, v162, v73
	ds_bpermute_b32 v192, v162, v68
	s_waitcnt lgkmcnt(3)
	v_pk_add_f32 v[182:183], v[222:223], v[188:189]
	global_load_dwordx4 v[188:191], v[204:205], off offset:512
	ds_bpermute_b32 v193, v162, v69
	s_waitcnt lgkmcnt(2)
	v_pk_add_f32 v[180:181], v[220:221], v[180:181]
	ds_bpermute_b32 v194, v162, v70
	ds_bpermute_b32 v195, v162, v71
	global_store_dwordx4 v[154:155], v[180:183], off offset:64
	global_load_dwordx4 v[180:183], v[204:205], off offset:576
	ds_bpermute_b32 v200, v162, v64
	ds_bpermute_b32 v196, v162, v66
	ds_bpermute_b32 v197, v162, v67
	ds_bpermute_b32 v201, v162, v65
	v_add_co_u32_e32 v206, vcc, s42, v152
	s_waitcnt lgkmcnt(4)
	v_pk_add_f32 v[194:195], v[226:227], v[194:195]
	v_pk_add_f32 v[192:193], v[224:225], v[192:193]
	v_addc_co_u32_e32 v207, vcc, 0, v153, vcc
	global_store_dwordx4 v[154:155], v[192:195], off offset:512
	global_load_dwordx4 v[192:195], v[206:207], off
	s_waitcnt lgkmcnt(1)
	v_pk_add_f32 v[130:131], v[130:131], v[196:197]
	s_waitcnt lgkmcnt(0)
	v_pk_add_f32 v[128:129], v[128:129], v[200:201]
	global_load_dwordx4 v[196:199], v[206:207], off offset:64
	ds_bpermute_b32 v202, v162, v62
	ds_bpermute_b32 v203, v162, v63
	global_store_dwordx4 v[154:155], v[128:131], off offset:576
	ds_bpermute_b32 v128, v162, v60
	ds_bpermute_b32 v129, v162, v61
	ds_bpermute_b32 v208, v162, v58
	ds_bpermute_b32 v209, v162, v59
	s_waitcnt vmcnt(18) lgkmcnt(4)
	v_pk_add_f32 v[130:131], v[166:167], v[202:203]
	ds_bpermute_b32 v154, v162, v56
	global_load_dwordx4 v[200:203], v[206:207], off offset:512
	ds_bpermute_b32 v155, v162, v57
	s_waitcnt lgkmcnt(4)
	v_pk_add_f32 v[128:129], v[164:165], v[128:129]
	global_load_dwordx4 v[164:167], v[206:207], off offset:576
	ds_bpermute_b32 v212, v162, v44
	global_store_dwordx4 v[156:157], v[128:131], off
	ds_bpermute_b32 v214, v162, v46
	ds_bpermute_b32 v215, v162, v47
	s_waitcnt vmcnt(19) lgkmcnt(5)
	v_pk_add_f32 v[130:131], v[174:175], v[208:209]
	v_add_co_u32_e32 v208, vcc, s43, v152
	s_waitcnt lgkmcnt(3)
	v_pk_add_f32 v[128:129], v[172:173], v[154:155]
	v_addc_co_u32_e32 v209, vcc, 0, v153, vcc
	global_store_dwordx4 v[156:157], v[128:131], off offset:64
	ds_bpermute_b32 v172, v162, v48
	ds_bpermute_b32 v173, v162, v49
	global_load_dwordx4 v[128:131], v[208:209], off
	global_load_dwordx4 v[152:155], v[208:209], off offset:64
	ds_bpermute_b32 v174, v162, v50
	ds_bpermute_b32 v175, v162, v51
	ds_bpermute_b32 v213, v162, v45
	s_waitcnt vmcnt(19) lgkmcnt(3)
	v_pk_add_f32 v[132:133], v[132:133], v[172:173]
	ds_bpermute_b32 v172, v162, v54
	ds_bpermute_b32 v173, v162, v55
	s_waitcnt lgkmcnt(3)
	v_pk_add_f32 v[134:135], v[134:135], v[174:175]
	global_store_dwordx4 v[156:157], v[132:135], off offset:512
	s_waitcnt vmcnt(16) lgkmcnt(0)
	v_pk_add_f32 v[174:175], v[178:179], v[172:173]
	v_pk_add_f32 v[134:135], v[138:139], v[214:215]
	v_pk_add_f32 v[132:133], v[136:137], v[212:213]
	global_store_dwordx4 v[156:157], v[132:135], off offset:576
	global_load_dwordx4 v[132:135], v[208:209], off offset:512
	ds_bpermute_b32 v156, v162, v52
	global_load_dwordx4 v[136:139], v[208:209], off offset:576
	ds_bpermute_b32 v157, v162, v53
	ds_bpermute_b32 v212, v162, v40
	ds_bpermute_b32 v214, v162, v42
	ds_bpermute_b32 v215, v162, v43
	ds_bpermute_b32 v213, v162, v41
	s_waitcnt lgkmcnt(4)
	v_pk_add_f32 v[172:173], v[176:177], v[156:157]
	global_store_dwordx4 v[204:205], v[172:175], off
	ds_bpermute_b32 v156, v162, v32
	ds_bpermute_b32 v157, v162, v33
	s_waitcnt vmcnt(19) lgkmcnt(3)
	v_pk_add_f32 v[174:175], v[186:187], v[214:215]
	s_waitcnt lgkmcnt(2)
	v_pk_add_f32 v[172:173], v[184:185], v[212:213]
	global_store_dwordx4 v[204:205], v[172:175], off offset:64
	ds_bpermute_b32 v172, v162, v34
	ds_bpermute_b32 v173, v162, v35
	ds_bpermute_b32 v176, v162, v28
	ds_bpermute_b32 v178, v162, v30
	ds_bpermute_b32 v179, v162, v31
	ds_bpermute_b32 v177, v162, v29
	s_waitcnt vmcnt(18) lgkmcnt(4)
	v_pk_add_f32 v[174:175], v[190:191], v[172:173]
	v_pk_add_f32 v[172:173], v[188:189], v[156:157]
	global_store_dwordx4 v[204:205], v[172:175], off offset:512
	ds_bpermute_b32 v156, v162, v36
	ds_bpermute_b32 v157, v162, v37
	s_waitcnt vmcnt(17) lgkmcnt(3)
	v_pk_add_f32 v[174:175], v[182:183], v[178:179]
	s_waitcnt lgkmcnt(2)
	v_pk_add_f32 v[172:173], v[180:181], v[176:177]
	global_store_dwordx4 v[204:205], v[172:175], off offset:576
	ds_bpermute_b32 v172, v162, v38
	ds_bpermute_b32 v173, v162, v39
	ds_bpermute_b32 v176, v162, v24
	ds_bpermute_b32 v178, v162, v26
	ds_bpermute_b32 v179, v162, v27
	ds_bpermute_b32 v177, v162, v25
	s_waitcnt vmcnt(16) lgkmcnt(4)
	v_pk_add_f32 v[174:175], v[194:195], v[172:173]
	v_pk_add_f32 v[172:173], v[192:193], v[156:157]
	global_store_dwordx4 v[206:207], v[172:175], off
	ds_bpermute_b32 v156, v162, v16
	ds_bpermute_b32 v157, v162, v17
	s_waitcnt vmcnt(16) lgkmcnt(3)
	v_pk_add_f32 v[174:175], v[198:199], v[178:179]
	s_waitcnt lgkmcnt(2)
	v_pk_add_f32 v[172:173], v[196:197], v[176:177]
	ds_bpermute_b32 v176, v162, v12
	ds_bpermute_b32 v178, v162, v14
	ds_bpermute_b32 v179, v162, v15
	ds_bpermute_b32 v177, v162, v13
	global_store_dwordx4 v[206:207], v[172:175], off offset:64
	ds_bpermute_b32 v172, v162, v18
	ds_bpermute_b32 v173, v162, v19
	s_waitcnt vmcnt(14) lgkmcnt(3)
	v_pk_add_f32 v[166:167], v[166:167], v[178:179]
	s_waitcnt lgkmcnt(2)
	v_pk_add_f32 v[164:165], v[164:165], v[176:177]
	global_store_dwordx4 v[206:207], v[164:167], off offset:576
	ds_bpermute_b32 v164, v162, v22
	s_waitcnt lgkmcnt(1)
	v_pk_add_f32 v[174:175], v[202:203], v[172:173]
	v_pk_add_f32 v[172:173], v[200:201], v[156:157]
	ds_bpermute_b32 v156, v162, v20
	ds_bpermute_b32 v157, v162, v21
	ds_bpermute_b32 v165, v162, v23
	global_store_dwordx4 v[206:207], v[172:175], off offset:512
	ds_bpermute_b32 v166, v162, v8
	ds_bpermute_b32 v172, v162, v10
	ds_bpermute_b32 v173, v162, v11
	ds_bpermute_b32 v167, v162, v9
	s_waitcnt vmcnt(13) lgkmcnt(4)
	v_pk_add_f32 v[130:131], v[130:131], v[164:165]
	v_pk_add_f32 v[128:129], v[128:129], v[156:157]
	global_store_dwordx4 v[208:209], v[128:131], off
	s_waitcnt vmcnt(13) lgkmcnt(1)
	s_nop 0
	v_pk_add_f32 v[130:131], v[154:155], v[172:173]
	s_waitcnt lgkmcnt(0)
	v_pk_add_f32 v[128:129], v[152:153], v[166:167]
	global_store_dwordx4 v[208:209], v[128:131], off offset:64
	ds_bpermute_b32 v128, v162, v4
	ds_bpermute_b32 v129, v162, v5
	ds_bpermute_b32 v130, v162, v6
	ds_bpermute_b32 v131, v162, v7
	ds_bpermute_b32 v152, v162, v0
	ds_bpermute_b32 v154, v162, v2
	ds_bpermute_b32 v155, v162, v3
	ds_bpermute_b32 v153, v162, v1
	s_waitcnt vmcnt(11) lgkmcnt(4)
	v_pk_add_f32 v[130:131], v[134:135], v[130:131]
	v_pk_add_f32 v[128:129], v[132:133], v[128:129]
	global_store_dwordx4 v[208:209], v[128:131], off offset:512
	s_waitcnt vmcnt(11) lgkmcnt(1)
	s_nop 0
	v_pk_add_f32 v[130:131], v[138:139], v[154:155]
	s_waitcnt lgkmcnt(0)
	v_pk_add_f32 v[128:129], v[136:137], v[152:153]
	global_store_dwordx4 v[208:209], v[128:131], off offset:576
